# v079 + w_out/w_glu bf16 weight copies moved from the modulation phase into the idle tail of the in-projection phase (workgroups 208..255)
# speedup vs baseline: 1.0044x; 1.0044x over previous
_Z3fwd4Args:
	s_mov_b32 s100, 0
	s_movk_i32 s101, 0x4540
	s_mov_b64 s[70:71], s[0:1]
	s_load_dwordx4 s[60:63], s[0:1], 0xe0
	s_add_u32 s0, s70, 0xf0
	s_addc_u32 s1, s71, 0
	s_mov_b32 s76, s2
	v_writelane_b32 v253, s0, 0
	s_nop 1
	v_writelane_b32 v253, s1, 1
	s_movk_i32 s0, 0x80
	v_cmp_gt_u32_e32 vcc, s0, v0
	s_and_saveexec_b64 s[4:5], vcc
	v_lshl_add_u32 v1, v0, 2, 0
	v_add_u32_e32 v1, 0x23e00, v1
	v_mov_b32_e32 v2, 0
	ds_write_b32 v1, v2
	s_or_b64 exec, exec, s[4:5]
	s_load_dword s3, s[70:71], 0xf0
	s_waitcnt lgkmcnt(0)
	s_add_u32 s4, s60, 0x1000
	s_addc_u32 s5, s61, 0
	s_sub_i32 s1, s63, s62
	s_cmp_lt_i32 s1, 2
	s_mov_b32 s1, 0
	s_mov_b64 s[82:83], 0x1000
	s_mov_b32 s89, 0
	s_mov_b32 s0, 0
	v_cmp_eq_u32_e32 vcc, 0, v0
	v_writelane_b32 v253, s1, 2
	s_barrier
	s_cbranch_scc1 .LBB0_7
	s_getreg_b32 s0, hwreg(HW_REG_XCC_ID, 0, 4)
	s_and_b32 s0, s0, 15
	s_and_saveexec_b64 s[6:7], vcc
	s_cbranch_execz .LBB0_6
	s_mov_b64 s[8:9], exec
	v_mbcnt_lo_u32_b32 v1, s8, 0
	v_mbcnt_hi_u32_b32 v1, s9, v1
	v_cmp_eq_u32_e32 vcc, 0, v1
	s_and_b64 s[10:11], exec, vcc
	s_mov_b64 exec, s[10:11]
	s_cbranch_execz .LBB0_6
	s_lshl_b32 s1, s0, 8
	s_bcnt1_i32_b64 s2, s[8:9]
	v_mov_b32_e32 v1, s1
	v_mov_b32_e32 v2, s2
	global_atomic_add v1, v2, s[4:5] offset:1024

.Lmy_a_entry:
	s_waitcnt vmcnt(0)
	v_mov_b32_e32 v8, v0
	s_mov_b64 s[6:7], s[70:71]
	s_load_dwordx2 s[4:5], s[6:7], 0xe0
	v_readlane_b32 s8, v253, 3
	v_readfirstlane_b32 s0, v8
	v_readlane_b32 s9, v253, 4
	v_and_b32_e32 v16, 63, v8
	s_cmp_eq_u32 s100, 1
	s_cbranch_scc0 .Lmy_a_keep
	s_nop 3
	s_mov_b64 s[8:9], 0
.Lmy_a_keep:
	s_andn2_b64 vcc, exec, s[8:9]
	s_ashr_i32 s30, s0, 6
	s_cbranch_vccnz .LBB0_37
	v_ashrrev_i32_e32 v2, 31, v8
	v_lshrrev_b32_e32 v2, 26, v2
	s_waitcnt lgkmcnt(0)
	v_readlane_b32 s12, v255, 8
	v_add_u32_e32 v2, v8, v2
	s_load_dwordx4 s[48:51], s[6:7], 0x28
	s_load_dwordx2 s[8:9], s[6:7], 0x8
	s_load_dwordx2 s[10:11], s[6:7], 0x18
	s_mov_b32 s42, s12
	v_ashrrev_i32_e32 v6, 6, v2
	v_and_b32_e32 v2, 0xffffffc0, v2
	v_mad_u64_u32 v[4:5], s[42:43], s42, 5, v[6:7]
	s_mul_i32 s0, s12, 0xc000
	v_sub_u32_e32 v2, v8, v2
	s_waitcnt lgkmcnt(0)
	v_mov_b64_e32 v[10:11], s[4:5]
	s_mov_b32 s42, 0xc000
	v_readlane_b32 s13, v255, 9
	s_mul_i32 s46, s12, 0xc000000
	s_add_u32 s12, s50, s0
	v_ashrrev_i32_e32 v3, 31, v2
	v_mad_i64_i32 v[4:5], s[42:43], v4, s42, v[10:11]
	s_addc_u32 s13, s51, 0
	s_movk_i32 s0, 0x5000
	s_lshl_b32 s2, s30, 11
	s_mul_i32 s40, s30, 0x500
	v_lshl_add_u64 v[4:5], v[2:3], 2, v[4:5]
	v_max_i32_e32 v3, 0x4e00, v8
	v_cmp_gt_i32_e64 s[38:39], s0, v8
	s_lshl_b32 s0, s30, 9
	s_add_i32 s2, s2, 0
	s_add_i32 s40, s14, s40
	v_sub_u32_e32 v3, v3, v8
	s_mul_i32 s47, s30, 0x1800000
	v_add_u32_e32 v3, 0x1ff, v3
	s_mul_hi_i32 s0, s0, 0xc000
	s_add_u32 s46, s46, s47
	v_lshlrev_b32_e32 v10, 8, v6
	v_lshrrev_b32_e32 v6, 9, v3
	s_addc_u32 s0, 0, s0
	s_mov_b64 s[42:43], 0xaf40000
	v_add_u32_e32 v6, 1, v6
	s_add_u32 s46, s48, s46
	v_lshlrev_b32_e32 v194, 2, v16
	v_lshl_add_u64 v[4:5], v[4:5], 0, s[42:43]
	v_cmp_lt_u32_e64 s[42:43], s15, v3
	v_and_b32_e32 v3, 0xfffffe, v6
	s_addc_u32 s47, s49, s0
	v_add_u32_e32 v17, s40, v194
	s_movk_i32 s40, 0x140
	v_lshl_add_u32 v12, v2, 2, s14
	v_cmp_ne_u32_e64 s[44:45], v6, v3
	v_lshl_add_u64 v[6:7], s[46:47], 0, v[194:195]
	s_mov_b64 s[46:47], 0x54000
	v_readlane_b32 s0, v254, 30
	v_cmp_gt_i32_e64 s[40:41], s40, v8
	v_lshl_add_u32 v18, v3, 9, v8
	v_add_u32_e32 v9, 0x200, v8
	v_lshl_add_u32 v19, v8, 2, 0
	v_lshl_add_u64 v[6:7], v[6:7], 0, s[46:47]
	s_mov_b64 s[46:47], 0
	v_add_u32_e32 v20, v12, v10
	s_mov_b32 s48, s0
	s_mov_b32 s56, s76
	s_branch .LBB0_17

.LBB0_37:
	v_readlane_b32 s0, v253, 5
	s_add_i32 s2, s30, s0
	s_movk_i32 s101, 0x4540
	s_cmp_eq_u32 s100, 1
	s_cbranch_scc1 .Lmy_a_def
	s_cmpk_lg_i32 s3, 0x100
	s_cbranch_scc1 .Lmy_a_it
	s_movk_i32 s101, 0x3440
	s_branch .Lmy_a_it
.Lmy_a_def:
	s_lshl_b32 s2, s76, 3
	s_add_i32 s2, s2, s30
	s_addk_i32 s2, 0x2dc0
	s_movk_i32 s96, 0x180
.Lmy_a_it:
	s_cmp_ge_i32 s2, s101
	s_waitcnt lgkmcnt(0)
	s_barrier
	s_cbranch_scc1 .LBB0_88
	s_load_dwordx2 s[8:9], s[6:7], 0x38
	v_readlane_b32 s12, v255, 8
	s_load_dwordx2 s[10:11], s[6:7], 0xc8
	s_nop 0
	s_load_dwordx2 s[6:7], s[6:7], 0xa8
	v_readlane_b32 s13, v255, 9
	s_mul_i32 s0, s12, 0xd080000
	s_mov_b32 s13, s89
	s_waitcnt lgkmcnt(0)
	s_add_u32 s42, s8, s0
	s_addc_u32 s43, s9, 0
	s_lshl_b64 s[8:9], s[12:13], 26
	s_add_u32 s44, s10, s8
	s_addc_u32 s45, s11, s9
	s_lshl_b64 s[8:9], s[12:13], 22
	s_add_u32 s46, s6, s8
	s_addc_u32 s47, s7, s9
	s_lshl_b64 s[6:7], s[12:13], 21
	s_add_u32 s6, s4, s6
	s_mov_b32 s0, s12
	s_addc_u32 s7, s5, s7
	v_writelane_b32 v255, s0, 8
	s_lshl_b64 s[8:9], s[12:13], 25
	s_add_u32 s8, s4, s8
	v_writelane_b32 v255, s1, 9
	s_mul_i32 s0, s30, 0x4400
	s_addc_u32 s9, s5, s9
	s_add_i32 s10, s0, 0
	v_lshrrev_b32_e32 v11, 4, v16
	v_mov_b32_e32 v2, s10
	s_movk_i32 s11, 0x110
	v_and_b32_e32 v3, 7, v8
	v_mad_u32_u24 v31, v11, s11, v2
	v_lshrrev_b32_e32 v42, 3, v16
	s_movk_i32 s11, 0x880
	v_lshlrev_b32_e32 v5, 2, v3
	v_mad_u32_u24 v4, v3, s11, v2
	v_xor_b32_e32 v6, v5, v42
	v_lshl_add_u32 v43, v6, 2, v4
	v_bitop3_b32 v6, v42, v5, 8 bitop3:0x36
	v_lshl_add_u32 v45, v6, 2, v4
	v_bitop3_b32 v6, v42, v5, 16 bitop3:0x36
	v_lshl_add_u32 v47, v6, 2, v4
	v_bitop3_b32 v6, v42, v5, 24 bitop3:0x36
	v_lshl_add_u32 v49, v6, 2, v4
	v_bitop3_b32 v6, v42, v5, 32 bitop3:0x36
	v_lshlrev_b32_e32 v12, 3, v16
	v_lshl_add_u32 v51, v6, 2, v4
	v_bitop3_b32 v6, v42, v5, 40 bitop3:0x36
	v_and_b32_e32 v12, 56, v12
	v_lshlrev_b32_e32 v194, 4, v3
	v_lshl_add_u32 v53, v6, 2, v4
	v_bitop3_b32 v6, v42, v5, 48 bitop3:0x36
	v_mul_u32_u24_e32 v14, 0x84, v12
	v_lshlrev_b32_e32 v12, 1, v12
	v_mov_b32_e32 v13, v195
	v_lshlrev_b32_e32 v15, 2, v42
	v_lshl_add_u32 v55, v6, 2, v4
	v_lshrrev_b32_e32 v6, 5, v16
	v_lshl_add_u64 v[12:13], s[4:5], 0, v[12:13]
	v_add3_u32 v58, s10, v14, v15
	v_lshl_add_u64 v[14:15], s[4:5], 0, v[194:195]
	s_mov_b64 s[4:5], 0x100000
	v_lshl_add_u64 v[2:3], s[6:7], 0, v[194:195]
	s_mov_b64 s[6:7], 0xab00000
	v_bitop3_b32 v5, v42, v5, 56 bitop3:0x36
	v_and_b32_e32 v17, 31, v8
	v_lshl_add_u64 v[14:15], v[14:15], 0, s[4:5]
	s_mul_i32 s4, s30, 0xfff2f800
	v_readlane_b32 s5, v254, 24
	v_mul_u32_u24_e32 v21, 0x84, v6
	v_and_b32_e32 v7, 15, v8
	v_lshl_add_u64 v[2:3], v[2:3], 0, s[6:7]
	v_or_b32_e32 v44, 8, v42
	v_or_b32_e32 v46, 16, v42
	v_or_b32_e32 v48, 24, v42
	v_lshl_add_u32 v57, v5, 2, v4
	v_lshl_add_u64 v[4:5], s[8:9], 0, v[194:195]
	s_mov_b64 s[6:7], 0x6b00000
	v_lshlrev_b32_e32 v19, 2, v17
	s_add_i32 s4, s4, s5
	v_or_b32_e32 v21, s0, v21
	s_mul_i32 s30, s30, 0xd0800
	s_mul_i32 s0, s76, 0x684000
	v_lshlrev_b32_e32 v9, 2, v7
	v_lshlrev_b32_e32 v34, 4, v7
	v_lshl_add_u64 v[4:5], v[4:5], 0, s[6:7]
	v_add_u32_e32 v10, s10, v19
	s_mov_b64 s[6:7], 0xaf00000
	v_lshlrev_b32_e32 v16, 12, v42
	v_lshlrev_b32_e32 v18, 12, v44
	v_lshlrev_b32_e32 v20, 12, v46
	v_lshlrev_b32_e32 v22, 12, v48
	v_cmp_lt_u32_e64 s[38:39], 7, v7
	v_mov_b32_e32 v7, s4
	s_movk_i32 s4, 0xcbe0
	v_add3_u32 v61, v21, v19, 0
	s_add_i32 s0, s0, s30
	v_mul_u32_u24_e32 v19, 0x3420, v6
	v_xor_b32_e32 v35, 16, v34
	v_xor_b32_e32 v36, 32, v34
	v_xor_b32_e32 v37, 48, v34
	v_xor_b32_e32 v38, 64, v34
	v_xor_b32_e32 v39, 0x50, v34
	v_xor_b32_e32 v40, 0x60, v34
	v_xor_b32_e32 v41, 0x70, v34
	v_or_b32_e32 v50, 32, v42
	v_or_b32_e32 v52, 40, v42
	v_or_b32_e32 v54, 48, v42
	v_or_b32_e32 v56, 56, v42
	v_or_b32_e32 v8, 0x1c00, v17
	v_lshl_add_u64 v[12:13], v[12:13], 0, s[6:7]
	v_subrev_u32_e32 v59, 32, v9
	v_mad_i32_i24 v60, v6, s4, v7
	v_mov_b32_e32 v7, v6
	v_add3_u32 v62, s0, v19, v17
	s_mov_b32 s8, 0
	v_lshlrev_b32_e32 v16, 1, v16
	v_lshlrev_b32_e32 v18, 1, v18
	v_lshlrev_b32_e32 v20, 1, v20
	v_lshlrev_b32_e32 v22, 1, v22
	s_branch .LBB0_41

.LBB0_40:
	s_add_i32 s2, s2, s96
	s_add_i32 s8, s8, 1
	s_mul_i32 s0, s3, 0x684000
	s_cmp_lt_i32 s2, s101
	v_add_u32_e32 v62, s0, v62
	s_cbranch_scc0 .LBB0_88

.LBB0_88:
	s_cmp_eq_u32 s100, 1
	s_cbranch_scc0 .Lmy_a_norm
	s_mov_b32 s100, 0
	v_readlane_b32 s96, v254, 60
	s_branch .Lmy_c_ret

.LBB0_247:
	s_cmpk_lg_i32 s3, 0x100
	s_cbranch_scc1 .Lmy_c_ret
	s_cmpk_lt_i32 s76, 0xd0
	s_cbranch_scc1 .Lmy_c_ret
	s_mov_b32 s100, 1
	s_branch .Lmy_a_entry

.LBB0_695:
	v_lshl_add_u32 v148, s6, 8, v150
	s_lshl_b32 s0, s4, 8
	v_or_b32_e32 v149, s0, v152
	v_mov_b32_e32 v181, 0
	v_lshlrev_b32_e32 v180, 11, v148
	v_lshl_add_u32 v180, v149, 1, v180
	v_lshl_add_u64 v[142:143], s[40:41], 0, v[180:181]
	v_lshlrev_b32_e32 v180, 2, v149
	v_lshl_add_u64 v[178:179], s[46:47], 0, v[180:181]
	global_load_dwordx4 v[154:157], v[178:179], off
	global_load_dwordx4 v[158:161], v[178:179], off offset:16
	global_load_dwordx4 v[162:165], v[178:179], off offset:512
	global_load_dwordx4 v[166:169], v[178:179], off offset:528
	s_add_i32 s4, s0, 0x2400
	s_ashr_i32 s0, s4, 9
	s_mul_hi_i32 s4, s0, 0x1100000
	s_mul_i32 s0, s0, 0x1100000
	s_add_u32 s58, s65, s0
	s_addc_u32 s59, s66, s4
	v_and_b32_e32 v180, 0x1ff, v149
	v_lshlrev_b32_e32 v180, 1, v180
	v_lshl_add_u32 v180, v148, 10, v180
	v_lshl_add_u64 v[144:145], s[58:59], 0, v[180:181]
	v_lshlrev_b32_e32 v180, 13, v148
	v_lshl_add_u32 v180, v149, 1, v180
	v_add_u32_e32 v180, 0x1000, v180
	v_lshl_add_u64 v[146:147], s[44:45], 0, v[180:181]
	global_load_dwordx4 v[170:173], v[142:143], off
	global_load_dwordx4 v[174:177], v[144:145], off
	s_waitcnt vmcnt(2)
	v_pk_add_f32 v[126:127], v[126:127], v[154:155]
	v_pk_add_f32 v[122:123], v[122:123], v[158:159]
	v_pk_add_f32 v[128:129], v[128:129], v[156:157]
	v_pk_add_f32 v[124:125], v[124:125], v[160:161]
	v_pk_add_f32 v[118:119], v[118:119], v[162:163]
	v_pk_add_f32 v[114:115], v[114:115], v[166:167]
	v_pk_add_f32 v[120:121], v[120:121], v[164:165]
	v_pk_add_f32 v[116:117], v[116:117], v[168:169]
	v_pk_add_f32 v[110:111], v[110:111], v[154:155]
	v_pk_add_f32 v[106:107], v[106:107], v[158:159]
	v_pk_add_f32 v[112:113], v[112:113], v[156:157]
	v_pk_add_f32 v[108:109], v[108:109], v[160:161]
	v_pk_add_f32 v[102:103], v[102:103], v[162:163]
	v_pk_add_f32 v[98:99], v[98:99], v[166:167]
	v_pk_add_f32 v[104:105], v[104:105], v[164:165]
	v_pk_add_f32 v[100:101], v[100:101], v[168:169]
	v_pk_add_f32 v[94:95], v[94:95], v[154:155]
	v_pk_add_f32 v[90:91], v[90:91], v[158:159]
	v_pk_add_f32 v[96:97], v[96:97], v[156:157]
	v_pk_add_f32 v[92:93], v[92:93], v[160:161]
	v_pk_add_f32 v[86:87], v[86:87], v[162:163]
	v_pk_add_f32 v[82:83], v[82:83], v[166:167]
	v_pk_add_f32 v[88:89], v[88:89], v[164:165]
	v_pk_add_f32 v[84:85], v[84:85], v[168:169]
	v_pk_add_f32 v[78:79], v[78:79], v[154:155]
	v_pk_add_f32 v[74:75], v[74:75], v[158:159]
	v_pk_add_f32 v[80:81], v[80:81], v[156:157]
	v_pk_add_f32 v[76:77], v[76:77], v[160:161]
	v_pk_add_f32 v[70:71], v[70:71], v[162:163]
	v_pk_add_f32 v[66:67], v[66:67], v[166:167]
	v_pk_add_f32 v[72:73], v[72:73], v[164:165]
	v_pk_add_f32 v[68:69], v[68:69], v[168:169]
	v_pk_add_f32 v[62:63], v[62:63], v[154:155]
	v_pk_add_f32 v[58:59], v[58:59], v[158:159]
	v_pk_add_f32 v[64:65], v[64:65], v[156:157]
	v_pk_add_f32 v[60:61], v[60:61], v[160:161]
	v_pk_add_f32 v[54:55], v[54:55], v[162:163]
	v_pk_add_f32 v[50:51], v[50:51], v[166:167]
	v_pk_add_f32 v[56:57], v[56:57], v[164:165]
	v_pk_add_f32 v[52:53], v[52:53], v[168:169]
	v_pk_add_f32 v[46:47], v[46:47], v[154:155]
	v_pk_add_f32 v[42:43], v[42:43], v[158:159]
	v_pk_add_f32 v[48:49], v[48:49], v[156:157]
	v_pk_add_f32 v[44:45], v[44:45], v[160:161]
	v_pk_add_f32 v[38:39], v[38:39], v[162:163]
	v_pk_add_f32 v[34:35], v[34:35], v[166:167]
	v_pk_add_f32 v[40:41], v[40:41], v[164:165]
	v_pk_add_f32 v[36:37], v[36:37], v[168:169]
	v_pk_add_f32 v[30:31], v[30:31], v[154:155]
	v_pk_add_f32 v[26:27], v[26:27], v[158:159]
	v_pk_add_f32 v[32:33], v[32:33], v[156:157]
	v_pk_add_f32 v[28:29], v[28:29], v[160:161]
	v_pk_add_f32 v[22:23], v[22:23], v[162:163]
	v_pk_add_f32 v[18:19], v[18:19], v[166:167]
	v_pk_add_f32 v[24:25], v[24:25], v[164:165]
	v_pk_add_f32 v[20:21], v[20:21], v[168:169]
	v_pk_add_f32 v[14:15], v[14:15], v[154:155]
	v_pk_add_f32 v[10:11], v[10:11], v[158:159]
	v_pk_add_f32 v[16:17], v[16:17], v[156:157]
	v_pk_add_f32 v[12:13], v[12:13], v[160:161]
	v_pk_add_f32 v[6:7], v[6:7], v[162:163]
	v_pk_add_f32 v[2:3], v[2:3], v[166:167]
	v_pk_add_f32 v[8:9], v[8:9], v[164:165]
	v_pk_add_f32 v[4:5], v[4:5], v[168:169]
	global_load_dwordx4 v[154:157], v[142:143], off offset:256
	global_load_dwordx4 v[158:161], v[144:145], off offset:256
	s_mov_b64 s[58:59], 0x8000
	v_lshl_add_u64 v[142:143], v[142:143], 0, s[58:59]
	s_mov_b64 s[58:59], 0x4000
	v_lshl_add_u64 v[144:145], v[144:145], 0, s[58:59]
	global_load_dwordx4 v[162:165], v[142:143], off
	global_load_dwordx4 v[166:169], v[144:145], off
	s_waitcnt vmcnt(4)
	v_lshlrev_b32_e32 v178, 16, v170
	v_and_b32_e32 v170, 0xffff0000, v170
	v_lshlrev_b32_e32 v179, 16, v174
	v_and_b32_e32 v174, 0xffff0000, v174
	v_mul_f32_e32 v126, 0xbfb8aa3b, v126
	v_mul_f32_e32 v127, 0xbfb8aa3b, v127
	v_mul_f32_e32 v180, 0xbfb8aa3b, v179
	v_mul_f32_e32 v181, 0xbfb8aa3b, v174
	v_exp_f32_e32 v126, v126
	v_exp_f32_e32 v127, v127
	v_exp_f32_e32 v180, v180
	v_exp_f32_e32 v181, v181
	v_add_f32_e32 v126, 1.0, v126
	v_add_f32_e32 v127, 1.0, v127
	v_add_f32_e32 v180, 1.0, v180
	v_add_f32_e32 v181, 1.0, v181
	v_rcp_f32_e32 v126, v126
	v_rcp_f32_e32 v127, v127
	v_rcp_f32_e32 v180, v180
	v_rcp_f32_e32 v181, v181
	v_mul_f32_e32 v126, v126, v178
	v_mul_f32_e32 v127, v127, v170
	v_mul_f32_e32 v180, v180, v179
	v_mul_f32_e32 v181, v181, v174
	v_mul_f32_e32 v126, v126, v180
	v_mul_f32_e32 v127, v127, v181
	v_lshlrev_b32_e32 v178, 16, v171
	v_and_b32_e32 v171, 0xffff0000, v171
	v_lshlrev_b32_e32 v179, 16, v175
	v_and_b32_e32 v175, 0xffff0000, v175
	v_mul_f32_e32 v128, 0xbfb8aa3b, v128
	v_mul_f32_e32 v129, 0xbfb8aa3b, v129
	v_mul_f32_e32 v180, 0xbfb8aa3b, v179
	v_mul_f32_e32 v181, 0xbfb8aa3b, v175
	v_exp_f32_e32 v128, v128
	v_exp_f32_e32 v129, v129
	v_exp_f32_e32 v180, v180
	v_exp_f32_e32 v181, v181
	v_add_f32_e32 v128, 1.0, v128
	v_add_f32_e32 v129, 1.0, v129
	v_add_f32_e32 v180, 1.0, v180
	v_add_f32_e32 v181, 1.0, v181
	v_rcp_f32_e32 v128, v128
	v_rcp_f32_e32 v129, v129
	v_rcp_f32_e32 v180, v180
	v_rcp_f32_e32 v181, v181
	v_mul_f32_e32 v128, v128, v178
	v_mul_f32_e32 v129, v129, v171
	v_mul_f32_e32 v180, v180, v179
	v_mul_f32_e32 v181, v181, v175
	v_mul_f32_e32 v128, v128, v180
	v_mul_f32_e32 v129, v129, v181
	v_lshlrev_b32_e32 v178, 16, v172
	v_and_b32_e32 v172, 0xffff0000, v172
	v_lshlrev_b32_e32 v179, 16, v176
	v_and_b32_e32 v176, 0xffff0000, v176
	v_mul_f32_e32 v122, 0xbfb8aa3b, v122
	v_mul_f32_e32 v123, 0xbfb8aa3b, v123
	v_mul_f32_e32 v180, 0xbfb8aa3b, v179
	v_mul_f32_e32 v181, 0xbfb8aa3b, v176
	v_exp_f32_e32 v122, v122
	v_exp_f32_e32 v123, v123
	v_exp_f32_e32 v180, v180
	v_exp_f32_e32 v181, v181
	v_add_f32_e32 v122, 1.0, v122
	v_add_f32_e32 v123, 1.0, v123
	v_add_f32_e32 v180, 1.0, v180
	v_add_f32_e32 v181, 1.0, v181
	v_rcp_f32_e32 v122, v122
	v_rcp_f32_e32 v123, v123
	v_rcp_f32_e32 v180, v180
	v_rcp_f32_e32 v181, v181
	v_mul_f32_e32 v122, v122, v178
	v_mul_f32_e32 v123, v123, v172
	v_mul_f32_e32 v180, v180, v179
	v_mul_f32_e32 v181, v181, v176
	v_mul_f32_e32 v122, v122, v180
	v_mul_f32_e32 v123, v123, v181
	v_lshlrev_b32_e32 v178, 16, v173
	v_and_b32_e32 v173, 0xffff0000, v173
	v_lshlrev_b32_e32 v179, 16, v177
	v_and_b32_e32 v177, 0xffff0000, v177
	v_mul_f32_e32 v124, 0xbfb8aa3b, v124
	v_mul_f32_e32 v125, 0xbfb8aa3b, v125
	v_mul_f32_e32 v180, 0xbfb8aa3b, v179
	v_mul_f32_e32 v181, 0xbfb8aa3b, v177
	v_exp_f32_e32 v124, v124
	v_exp_f32_e32 v125, v125
	v_exp_f32_e32 v180, v180
	v_exp_f32_e32 v181, v181
	v_add_f32_e32 v124, 1.0, v124
	v_add_f32_e32 v125, 1.0, v125
	v_add_f32_e32 v180, 1.0, v180
	v_add_f32_e32 v181, 1.0, v181
	v_rcp_f32_e32 v124, v124
	v_rcp_f32_e32 v125, v125
	v_rcp_f32_e32 v180, v180
	v_rcp_f32_e32 v181, v181
	v_mul_f32_e32 v124, v124, v178
	v_mul_f32_e32 v125, v125, v173
	v_mul_f32_e32 v180, v180, v179
	v_mul_f32_e32 v181, v181, v177
	v_mul_f32_e32 v124, v124, v180
	v_mul_f32_e32 v125, v125, v181
	v_cvt_pk_bf16_f32 v126, v126, v127
	v_cvt_pk_bf16_f32 v127, v128, v129
	v_cvt_pk_bf16_f32 v128, v122, v123
	v_cvt_pk_bf16_f32 v129, v124, v125
	global_store_dwordx4 v[146:147], v[126:129], off
	global_load_dwordx4 v[170:173], v[142:143], off offset:256
	global_load_dwordx4 v[174:177], v[144:145], off offset:256
	s_waitcnt vmcnt(5)
	v_lshlrev_b32_e32 v178, 16, v154
	v_and_b32_e32 v154, 0xffff0000, v154
	v_lshlrev_b32_e32 v179, 16, v158
	v_and_b32_e32 v158, 0xffff0000, v158
	v_mul_f32_e32 v118, 0xbfb8aa3b, v118
	v_mul_f32_e32 v119, 0xbfb8aa3b, v119
	v_mul_f32_e32 v180, 0xbfb8aa3b, v179
	v_mul_f32_e32 v181, 0xbfb8aa3b, v158
	v_exp_f32_e32 v118, v118
	v_exp_f32_e32 v119, v119
	v_exp_f32_e32 v180, v180
	v_exp_f32_e32 v181, v181
	v_add_f32_e32 v118, 1.0, v118
	v_add_f32_e32 v119, 1.0, v119
	v_add_f32_e32 v180, 1.0, v180
	v_add_f32_e32 v181, 1.0, v181
	v_rcp_f32_e32 v118, v118
	v_rcp_f32_e32 v119, v119
	v_rcp_f32_e32 v180, v180
	v_rcp_f32_e32 v181, v181
	v_mul_f32_e32 v118, v118, v178
	v_mul_f32_e32 v119, v119, v154
	v_mul_f32_e32 v180, v180, v179
	v_mul_f32_e32 v181, v181, v158
	v_mul_f32_e32 v118, v118, v180
	v_mul_f32_e32 v119, v119, v181
	v_lshlrev_b32_e32 v178, 16, v155
	v_and_b32_e32 v155, 0xffff0000, v155
	v_lshlrev_b32_e32 v179, 16, v159
	v_and_b32_e32 v159, 0xffff0000, v159
	v_mul_f32_e32 v120, 0xbfb8aa3b, v120
	v_mul_f32_e32 v121, 0xbfb8aa3b, v121
	v_mul_f32_e32 v180, 0xbfb8aa3b, v179
	v_mul_f32_e32 v181, 0xbfb8aa3b, v159
	v_exp_f32_e32 v120, v120
	v_exp_f32_e32 v121, v121
	v_exp_f32_e32 v180, v180
	v_exp_f32_e32 v181, v181
	v_add_f32_e32 v120, 1.0, v120
	v_add_f32_e32 v121, 1.0, v121
	v_add_f32_e32 v180, 1.0, v180
	v_add_f32_e32 v181, 1.0, v181
	v_rcp_f32_e32 v120, v120
	v_rcp_f32_e32 v121, v121
	v_rcp_f32_e32 v180, v180
	v_rcp_f32_e32 v181, v181
	v_mul_f32_e32 v120, v120, v178
	v_mul_f32_e32 v121, v121, v155
	v_mul_f32_e32 v180, v180, v179
	v_mul_f32_e32 v181, v181, v159
	v_mul_f32_e32 v120, v120, v180
	v_mul_f32_e32 v121, v121, v181
	v_lshlrev_b32_e32 v178, 16, v156
	v_and_b32_e32 v156, 0xffff0000, v156
	v_lshlrev_b32_e32 v179, 16, v160
	v_and_b32_e32 v160, 0xffff0000, v160
	v_mul_f32_e32 v114, 0xbfb8aa3b, v114
	v_mul_f32_e32 v115, 0xbfb8aa3b, v115
	v_mul_f32_e32 v180, 0xbfb8aa3b, v179
	v_mul_f32_e32 v181, 0xbfb8aa3b, v160
	v_exp_f32_e32 v114, v114
	v_exp_f32_e32 v115, v115
	v_exp_f32_e32 v180, v180
	v_exp_f32_e32 v181, v181
	v_add_f32_e32 v114, 1.0, v114
	v_add_f32_e32 v115, 1.0, v115
	v_add_f32_e32 v180, 1.0, v180
	v_add_f32_e32 v181, 1.0, v181
	v_rcp_f32_e32 v114, v114
	v_rcp_f32_e32 v115, v115
	v_rcp_f32_e32 v180, v180
	v_rcp_f32_e32 v181, v181
	v_mul_f32_e32 v114, v114, v178
	v_mul_f32_e32 v115, v115, v156
	v_mul_f32_e32 v180, v180, v179
	v_mul_f32_e32 v181, v181, v160
	v_mul_f32_e32 v114, v114, v180
	v_mul_f32_e32 v115, v115, v181
	v_lshlrev_b32_e32 v178, 16, v157
	v_and_b32_e32 v157, 0xffff0000, v157
	v_lshlrev_b32_e32 v179, 16, v161
	v_and_b32_e32 v161, 0xffff0000, v161
	v_mul_f32_e32 v116, 0xbfb8aa3b, v116
	v_mul_f32_e32 v117, 0xbfb8aa3b, v117
	v_mul_f32_e32 v180, 0xbfb8aa3b, v179
	v_mul_f32_e32 v181, 0xbfb8aa3b, v161
	v_exp_f32_e32 v116, v116
	v_exp_f32_e32 v117, v117
	v_exp_f32_e32 v180, v180
	v_exp_f32_e32 v181, v181
	v_add_f32_e32 v116, 1.0, v116
	v_add_f32_e32 v117, 1.0, v117
	v_add_f32_e32 v180, 1.0, v180
	v_add_f32_e32 v181, 1.0, v181
	v_rcp_f32_e32 v116, v116
	v_rcp_f32_e32 v117, v117
	v_rcp_f32_e32 v180, v180
	v_rcp_f32_e32 v181, v181
	v_mul_f32_e32 v116, v116, v178
	v_mul_f32_e32 v117, v117, v157
	v_mul_f32_e32 v180, v180, v179
	v_mul_f32_e32 v181, v181, v161
	v_mul_f32_e32 v116, v116, v180
	v_mul_f32_e32 v117, v117, v181
	v_cvt_pk_bf16_f32 v118, v118, v119
	v_cvt_pk_bf16_f32 v119, v120, v121
	v_cvt_pk_bf16_f32 v120, v114, v115
	v_cvt_pk_bf16_f32 v121, v116, v117
	global_store_dwordx4 v[146:147], v[118:121], off offset:256
	s_mov_b64 s[58:59], 0x20000
	v_lshl_add_u64 v[146:147], v[146:147], 0, s[58:59]
	s_mov_b64 s[58:59], 0x8000
	v_lshl_add_u64 v[142:143], v[142:143], 0, s[58:59]
	s_mov_b64 s[58:59], 0x4000
	v_lshl_add_u64 v[144:145], v[144:145], 0, s[58:59]
	global_load_dwordx4 v[154:157], v[142:143], off
	global_load_dwordx4 v[158:161], v[144:145], off
	s_waitcnt vmcnt(6)
	v_lshlrev_b32_e32 v178, 16, v162
	v_and_b32_e32 v162, 0xffff0000, v162
	v_lshlrev_b32_e32 v179, 16, v166
	v_and_b32_e32 v166, 0xffff0000, v166
	v_mul_f32_e32 v110, 0xbfb8aa3b, v110
	v_mul_f32_e32 v111, 0xbfb8aa3b, v111
	v_mul_f32_e32 v180, 0xbfb8aa3b, v179
	v_mul_f32_e32 v181, 0xbfb8aa3b, v166
	v_exp_f32_e32 v110, v110
	v_exp_f32_e32 v111, v111
	v_exp_f32_e32 v180, v180
	v_exp_f32_e32 v181, v181
	v_add_f32_e32 v110, 1.0, v110
	v_add_f32_e32 v111, 1.0, v111
	v_add_f32_e32 v180, 1.0, v180
	v_add_f32_e32 v181, 1.0, v181
	v_rcp_f32_e32 v110, v110
	v_rcp_f32_e32 v111, v111
	v_rcp_f32_e32 v180, v180
	v_rcp_f32_e32 v181, v181
	v_mul_f32_e32 v110, v110, v178
	v_mul_f32_e32 v111, v111, v162
	v_mul_f32_e32 v180, v180, v179
	v_mul_f32_e32 v181, v181, v166
	v_mul_f32_e32 v110, v110, v180
	v_mul_f32_e32 v111, v111, v181
	v_lshlrev_b32_e32 v178, 16, v163
	v_and_b32_e32 v163, 0xffff0000, v163
	v_lshlrev_b32_e32 v179, 16, v167
	v_and_b32_e32 v167, 0xffff0000, v167
	v_mul_f32_e32 v112, 0xbfb8aa3b, v112
	v_mul_f32_e32 v113, 0xbfb8aa3b, v113
	v_mul_f32_e32 v180, 0xbfb8aa3b, v179
	v_mul_f32_e32 v181, 0xbfb8aa3b, v167
	v_exp_f32_e32 v112, v112
	v_exp_f32_e32 v113, v113
	v_exp_f32_e32 v180, v180
	v_exp_f32_e32 v181, v181
	v_add_f32_e32 v112, 1.0, v112
	v_add_f32_e32 v113, 1.0, v113
	v_add_f32_e32 v180, 1.0, v180
	v_add_f32_e32 v181, 1.0, v181
	v_rcp_f32_e32 v112, v112
	v_rcp_f32_e32 v113, v113
	v_rcp_f32_e32 v180, v180
	v_rcp_f32_e32 v181, v181
	v_mul_f32_e32 v112, v112, v178
	v_mul_f32_e32 v113, v113, v163
	v_mul_f32_e32 v180, v180, v179
	v_mul_f32_e32 v181, v181, v167
	v_mul_f32_e32 v112, v112, v180
	v_mul_f32_e32 v113, v113, v181
	v_lshlrev_b32_e32 v178, 16, v164
	v_and_b32_e32 v164, 0xffff0000, v164
	v_lshlrev_b32_e32 v179, 16, v168
	v_and_b32_e32 v168, 0xffff0000, v168
	v_mul_f32_e32 v106, 0xbfb8aa3b, v106
	v_mul_f32_e32 v107, 0xbfb8aa3b, v107
	v_mul_f32_e32 v180, 0xbfb8aa3b, v179
	v_mul_f32_e32 v181, 0xbfb8aa3b, v168
	v_exp_f32_e32 v106, v106
	v_exp_f32_e32 v107, v107
	v_exp_f32_e32 v180, v180
	v_exp_f32_e32 v181, v181
	v_add_f32_e32 v106, 1.0, v106
	v_add_f32_e32 v107, 1.0, v107
	v_add_f32_e32 v180, 1.0, v180
	v_add_f32_e32 v181, 1.0, v181
	v_rcp_f32_e32 v106, v106
	v_rcp_f32_e32 v107, v107
	v_rcp_f32_e32 v180, v180
	v_rcp_f32_e32 v181, v181
	v_mul_f32_e32 v106, v106, v178
	v_mul_f32_e32 v107, v107, v164
	v_mul_f32_e32 v180, v180, v179
	v_mul_f32_e32 v181, v181, v168
	v_mul_f32_e32 v106, v106, v180
	v_mul_f32_e32 v107, v107, v181
	v_lshlrev_b32_e32 v178, 16, v165
	v_and_b32_e32 v165, 0xffff0000, v165
	v_lshlrev_b32_e32 v179, 16, v169
	v_and_b32_e32 v169, 0xffff0000, v169
	v_mul_f32_e32 v108, 0xbfb8aa3b, v108
	v_mul_f32_e32 v109, 0xbfb8aa3b, v109
	v_mul_f32_e32 v180, 0xbfb8aa3b, v179
	v_mul_f32_e32 v181, 0xbfb8aa3b, v169
	v_exp_f32_e32 v108, v108
	v_exp_f32_e32 v109, v109
	v_exp_f32_e32 v180, v180
	v_exp_f32_e32 v181, v181
	v_add_f32_e32 v108, 1.0, v108
	v_add_f32_e32 v109, 1.0, v109
	v_add_f32_e32 v180, 1.0, v180
	v_add_f32_e32 v181, 1.0, v181
	v_rcp_f32_e32 v108, v108
	v_rcp_f32_e32 v109, v109
	v_rcp_f32_e32 v180, v180
	v_rcp_f32_e32 v181, v181
	v_mul_f32_e32 v108, v108, v178
	v_mul_f32_e32 v109, v109, v165
	v_mul_f32_e32 v180, v180, v179
	v_mul_f32_e32 v181, v181, v169
	v_mul_f32_e32 v108, v108, v180
	v_mul_f32_e32 v109, v109, v181
	v_cvt_pk_bf16_f32 v110, v110, v111
	v_cvt_pk_bf16_f32 v111, v112, v113
	v_cvt_pk_bf16_f32 v112, v106, v107
	v_cvt_pk_bf16_f32 v113, v108, v109
	global_store_dwordx4 v[146:147], v[110:113], off
	global_load_dwordx4 v[162:165], v[142:143], off offset:256
	global_load_dwordx4 v[166:169], v[144:145], off offset:256
	s_waitcnt vmcnt(6)
	v_lshlrev_b32_e32 v178, 16, v170
	v_and_b32_e32 v170, 0xffff0000, v170
	v_lshlrev_b32_e32 v179, 16, v174
	v_and_b32_e32 v174, 0xffff0000, v174
	v_mul_f32_e32 v102, 0xbfb8aa3b, v102
	v_mul_f32_e32 v103, 0xbfb8aa3b, v103
	v_mul_f32_e32 v180, 0xbfb8aa3b, v179
	v_mul_f32_e32 v181, 0xbfb8aa3b, v174
	v_exp_f32_e32 v102, v102
	v_exp_f32_e32 v103, v103
	v_exp_f32_e32 v180, v180
	v_exp_f32_e32 v181, v181
	v_add_f32_e32 v102, 1.0, v102
	v_add_f32_e32 v103, 1.0, v103
	v_add_f32_e32 v180, 1.0, v180
	v_add_f32_e32 v181, 1.0, v181
	v_rcp_f32_e32 v102, v102
	v_rcp_f32_e32 v103, v103
	v_rcp_f32_e32 v180, v180
	v_rcp_f32_e32 v181, v181
	v_mul_f32_e32 v102, v102, v178
	v_mul_f32_e32 v103, v103, v170
	v_mul_f32_e32 v180, v180, v179
	v_mul_f32_e32 v181, v181, v174
	v_mul_f32_e32 v102, v102, v180
	v_mul_f32_e32 v103, v103, v181
	v_lshlrev_b32_e32 v178, 16, v171
	v_and_b32_e32 v171, 0xffff0000, v171
	v_lshlrev_b32_e32 v179, 16, v175
	v_and_b32_e32 v175, 0xffff0000, v175
	v_mul_f32_e32 v104, 0xbfb8aa3b, v104
	v_mul_f32_e32 v105, 0xbfb8aa3b, v105
	v_mul_f32_e32 v180, 0xbfb8aa3b, v179
	v_mul_f32_e32 v181, 0xbfb8aa3b, v175
	v_exp_f32_e32 v104, v104
	v_exp_f32_e32 v105, v105
	v_exp_f32_e32 v180, v180
	v_exp_f32_e32 v181, v181
	v_add_f32_e32 v104, 1.0, v104
	v_add_f32_e32 v105, 1.0, v105
	v_add_f32_e32 v180, 1.0, v180
	v_add_f32_e32 v181, 1.0, v181
	v_rcp_f32_e32 v104, v104
	v_rcp_f32_e32 v105, v105
	v_rcp_f32_e32 v180, v180
	v_rcp_f32_e32 v181, v181
	v_mul_f32_e32 v104, v104, v178
	v_mul_f32_e32 v105, v105, v171
	v_mul_f32_e32 v180, v180, v179
	v_mul_f32_e32 v181, v181, v175
	v_mul_f32_e32 v104, v104, v180
	v_mul_f32_e32 v105, v105, v181
	v_lshlrev_b32_e32 v178, 16, v172
	v_and_b32_e32 v172, 0xffff0000, v172
	v_lshlrev_b32_e32 v179, 16, v176
	v_and_b32_e32 v176, 0xffff0000, v176
	v_mul_f32_e32 v98, 0xbfb8aa3b, v98
	v_mul_f32_e32 v99, 0xbfb8aa3b, v99
	v_mul_f32_e32 v180, 0xbfb8aa3b, v179
	v_mul_f32_e32 v181, 0xbfb8aa3b, v176
	v_exp_f32_e32 v98, v98
	v_exp_f32_e32 v99, v99
	v_exp_f32_e32 v180, v180
	v_exp_f32_e32 v181, v181
	v_add_f32_e32 v98, 1.0, v98
	v_add_f32_e32 v99, 1.0, v99
	v_add_f32_e32 v180, 1.0, v180
	v_add_f32_e32 v181, 1.0, v181
	v_rcp_f32_e32 v98, v98
	v_rcp_f32_e32 v99, v99
	v_rcp_f32_e32 v180, v180
	v_rcp_f32_e32 v181, v181
	v_mul_f32_e32 v98, v98, v178
	v_mul_f32_e32 v99, v99, v172
	v_mul_f32_e32 v180, v180, v179
	v_mul_f32_e32 v181, v181, v176
	v_mul_f32_e32 v98, v98, v180
	v_mul_f32_e32 v99, v99, v181
	v_lshlrev_b32_e32 v178, 16, v173
	v_and_b32_e32 v173, 0xffff0000, v173
	v_lshlrev_b32_e32 v179, 16, v177
	v_and_b32_e32 v177, 0xffff0000, v177
	v_mul_f32_e32 v100, 0xbfb8aa3b, v100
	v_mul_f32_e32 v101, 0xbfb8aa3b, v101
	v_mul_f32_e32 v180, 0xbfb8aa3b, v179
	v_mul_f32_e32 v181, 0xbfb8aa3b, v177
	v_exp_f32_e32 v100, v100
	v_exp_f32_e32 v101, v101
	v_exp_f32_e32 v180, v180
	v_exp_f32_e32 v181, v181
	v_add_f32_e32 v100, 1.0, v100
	v_add_f32_e32 v101, 1.0, v101
	v_add_f32_e32 v180, 1.0, v180
	v_add_f32_e32 v181, 1.0, v181
	v_rcp_f32_e32 v100, v100
	v_rcp_f32_e32 v101, v101
	v_rcp_f32_e32 v180, v180
	v_rcp_f32_e32 v181, v181
	v_mul_f32_e32 v100, v100, v178
	v_mul_f32_e32 v101, v101, v173
	v_mul_f32_e32 v180, v180, v179
	v_mul_f32_e32 v181, v181, v177
	v_mul_f32_e32 v100, v100, v180
	v_mul_f32_e32 v101, v101, v181
	v_cvt_pk_bf16_f32 v102, v102, v103
	v_cvt_pk_bf16_f32 v103, v104, v105
	v_cvt_pk_bf16_f32 v104, v98, v99
	v_cvt_pk_bf16_f32 v105, v100, v101
	global_store_dwordx4 v[146:147], v[102:105], off offset:256
	s_mov_b64 s[58:59], 0x20000
	v_lshl_add_u64 v[146:147], v[146:147], 0, s[58:59]
	s_mov_b64 s[58:59], 0x8000
	v_lshl_add_u64 v[142:143], v[142:143], 0, s[58:59]
	s_mov_b64 s[58:59], 0x4000
	v_lshl_add_u64 v[144:145], v[144:145], 0, s[58:59]
	global_load_dwordx4 v[170:173], v[142:143], off
	global_load_dwordx4 v[174:177], v[144:145], off
	s_waitcnt vmcnt(6)
	v_lshlrev_b32_e32 v178, 16, v154
	v_and_b32_e32 v154, 0xffff0000, v154
	v_lshlrev_b32_e32 v179, 16, v158
	v_and_b32_e32 v158, 0xffff0000, v158
	v_mul_f32_e32 v94, 0xbfb8aa3b, v94
	v_mul_f32_e32 v95, 0xbfb8aa3b, v95
	v_mul_f32_e32 v180, 0xbfb8aa3b, v179
	v_mul_f32_e32 v181, 0xbfb8aa3b, v158
	v_exp_f32_e32 v94, v94
	v_exp_f32_e32 v95, v95
	v_exp_f32_e32 v180, v180
	v_exp_f32_e32 v181, v181
	v_add_f32_e32 v94, 1.0, v94
	v_add_f32_e32 v95, 1.0, v95
	v_add_f32_e32 v180, 1.0, v180
	v_add_f32_e32 v181, 1.0, v181
	v_rcp_f32_e32 v94, v94
	v_rcp_f32_e32 v95, v95
	v_rcp_f32_e32 v180, v180
	v_rcp_f32_e32 v181, v181
	v_mul_f32_e32 v94, v94, v178
	v_mul_f32_e32 v95, v95, v154
	v_mul_f32_e32 v180, v180, v179
	v_mul_f32_e32 v181, v181, v158
	v_mul_f32_e32 v94, v94, v180
	v_mul_f32_e32 v95, v95, v181
	v_lshlrev_b32_e32 v178, 16, v155
	v_and_b32_e32 v155, 0xffff0000, v155
	v_lshlrev_b32_e32 v179, 16, v159
	v_and_b32_e32 v159, 0xffff0000, v159
	v_mul_f32_e32 v96, 0xbfb8aa3b, v96
	v_mul_f32_e32 v97, 0xbfb8aa3b, v97
	v_mul_f32_e32 v180, 0xbfb8aa3b, v179
	v_mul_f32_e32 v181, 0xbfb8aa3b, v159
	v_exp_f32_e32 v96, v96
	v_exp_f32_e32 v97, v97
	v_exp_f32_e32 v180, v180
	v_exp_f32_e32 v181, v181
	v_add_f32_e32 v96, 1.0, v96
	v_add_f32_e32 v97, 1.0, v97
	v_add_f32_e32 v180, 1.0, v180
	v_add_f32_e32 v181, 1.0, v181
	v_rcp_f32_e32 v96, v96
	v_rcp_f32_e32 v97, v97
	v_rcp_f32_e32 v180, v180
	v_rcp_f32_e32 v181, v181
	v_mul_f32_e32 v96, v96, v178
	v_mul_f32_e32 v97, v97, v155
	v_mul_f32_e32 v180, v180, v179
	v_mul_f32_e32 v181, v181, v159
	v_mul_f32_e32 v96, v96, v180
	v_mul_f32_e32 v97, v97, v181
	v_lshlrev_b32_e32 v178, 16, v156
	v_and_b32_e32 v156, 0xffff0000, v156
	v_lshlrev_b32_e32 v179, 16, v160
	v_and_b32_e32 v160, 0xffff0000, v160
	v_mul_f32_e32 v90, 0xbfb8aa3b, v90
	v_mul_f32_e32 v91, 0xbfb8aa3b, v91
	v_mul_f32_e32 v180, 0xbfb8aa3b, v179
	v_mul_f32_e32 v181, 0xbfb8aa3b, v160
	v_exp_f32_e32 v90, v90
	v_exp_f32_e32 v91, v91
	v_exp_f32_e32 v180, v180
	v_exp_f32_e32 v181, v181
	v_add_f32_e32 v90, 1.0, v90
	v_add_f32_e32 v91, 1.0, v91
	v_add_f32_e32 v180, 1.0, v180
	v_add_f32_e32 v181, 1.0, v181
	v_rcp_f32_e32 v90, v90
	v_rcp_f32_e32 v91, v91
	v_rcp_f32_e32 v180, v180
	v_rcp_f32_e32 v181, v181
	v_mul_f32_e32 v90, v90, v178
	v_mul_f32_e32 v91, v91, v156
	v_mul_f32_e32 v180, v180, v179
	v_mul_f32_e32 v181, v181, v160
	v_mul_f32_e32 v90, v90, v180
	v_mul_f32_e32 v91, v91, v181
	v_lshlrev_b32_e32 v178, 16, v157
	v_and_b32_e32 v157, 0xffff0000, v157
	v_lshlrev_b32_e32 v179, 16, v161
	v_and_b32_e32 v161, 0xffff0000, v161
	v_mul_f32_e32 v92, 0xbfb8aa3b, v92
	v_mul_f32_e32 v93, 0xbfb8aa3b, v93
	v_mul_f32_e32 v180, 0xbfb8aa3b, v179
	v_mul_f32_e32 v181, 0xbfb8aa3b, v161
	v_exp_f32_e32 v92, v92
	v_exp_f32_e32 v93, v93
	v_exp_f32_e32 v180, v180
	v_exp_f32_e32 v181, v181
	v_add_f32_e32 v92, 1.0, v92
	v_add_f32_e32 v93, 1.0, v93
	v_add_f32_e32 v180, 1.0, v180
	v_add_f32_e32 v181, 1.0, v181
	v_rcp_f32_e32 v92, v92
	v_rcp_f32_e32 v93, v93
	v_rcp_f32_e32 v180, v180
	v_rcp_f32_e32 v181, v181
	v_mul_f32_e32 v92, v92, v178
	v_mul_f32_e32 v93, v93, v157
	v_mul_f32_e32 v180, v180, v179
	v_mul_f32_e32 v181, v181, v161
	v_mul_f32_e32 v92, v92, v180
	v_mul_f32_e32 v93, v93, v181
	v_cvt_pk_bf16_f32 v94, v94, v95
	v_cvt_pk_bf16_f32 v95, v96, v97
	v_cvt_pk_bf16_f32 v96, v90, v91
	v_cvt_pk_bf16_f32 v97, v92, v93
	global_store_dwordx4 v[146:147], v[94:97], off
	global_load_dwordx4 v[154:157], v[142:143], off offset:256
	global_load_dwordx4 v[158:161], v[144:145], off offset:256
	s_waitcnt vmcnt(6)
	v_lshlrev_b32_e32 v178, 16, v162
	v_and_b32_e32 v162, 0xffff0000, v162
	v_lshlrev_b32_e32 v179, 16, v166
	v_and_b32_e32 v166, 0xffff0000, v166
	v_mul_f32_e32 v86, 0xbfb8aa3b, v86
	v_mul_f32_e32 v87, 0xbfb8aa3b, v87
	v_mul_f32_e32 v180, 0xbfb8aa3b, v179
	v_mul_f32_e32 v181, 0xbfb8aa3b, v166
	v_exp_f32_e32 v86, v86
	v_exp_f32_e32 v87, v87
	v_exp_f32_e32 v180, v180
	v_exp_f32_e32 v181, v181
	v_add_f32_e32 v86, 1.0, v86
	v_add_f32_e32 v87, 1.0, v87
	v_add_f32_e32 v180, 1.0, v180
	v_add_f32_e32 v181, 1.0, v181
	v_rcp_f32_e32 v86, v86
	v_rcp_f32_e32 v87, v87
	v_rcp_f32_e32 v180, v180
	v_rcp_f32_e32 v181, v181
	v_mul_f32_e32 v86, v86, v178
	v_mul_f32_e32 v87, v87, v162
	v_mul_f32_e32 v180, v180, v179
	v_mul_f32_e32 v181, v181, v166
	v_mul_f32_e32 v86, v86, v180
	v_mul_f32_e32 v87, v87, v181
	v_lshlrev_b32_e32 v178, 16, v163
	v_and_b32_e32 v163, 0xffff0000, v163
	v_lshlrev_b32_e32 v179, 16, v167
	v_and_b32_e32 v167, 0xffff0000, v167
	v_mul_f32_e32 v88, 0xbfb8aa3b, v88
	v_mul_f32_e32 v89, 0xbfb8aa3b, v89
	v_mul_f32_e32 v180, 0xbfb8aa3b, v179
	v_mul_f32_e32 v181, 0xbfb8aa3b, v167
	v_exp_f32_e32 v88, v88
	v_exp_f32_e32 v89, v89
	v_exp_f32_e32 v180, v180
	v_exp_f32_e32 v181, v181
	v_add_f32_e32 v88, 1.0, v88
	v_add_f32_e32 v89, 1.0, v89
	v_add_f32_e32 v180, 1.0, v180
	v_add_f32_e32 v181, 1.0, v181
	v_rcp_f32_e32 v88, v88
	v_rcp_f32_e32 v89, v89
	v_rcp_f32_e32 v180, v180
	v_rcp_f32_e32 v181, v181
	v_mul_f32_e32 v88, v88, v178
	v_mul_f32_e32 v89, v89, v163
	v_mul_f32_e32 v180, v180, v179
	v_mul_f32_e32 v181, v181, v167
	v_mul_f32_e32 v88, v88, v180
	v_mul_f32_e32 v89, v89, v181
	v_lshlrev_b32_e32 v178, 16, v164
	v_and_b32_e32 v164, 0xffff0000, v164
	v_lshlrev_b32_e32 v179, 16, v168
	v_and_b32_e32 v168, 0xffff0000, v168
	v_mul_f32_e32 v82, 0xbfb8aa3b, v82
	v_mul_f32_e32 v83, 0xbfb8aa3b, v83
	v_mul_f32_e32 v180, 0xbfb8aa3b, v179
	v_mul_f32_e32 v181, 0xbfb8aa3b, v168
	v_exp_f32_e32 v82, v82
	v_exp_f32_e32 v83, v83
	v_exp_f32_e32 v180, v180
	v_exp_f32_e32 v181, v181
	v_add_f32_e32 v82, 1.0, v82
	v_add_f32_e32 v83, 1.0, v83
	v_add_f32_e32 v180, 1.0, v180
	v_add_f32_e32 v181, 1.0, v181
	v_rcp_f32_e32 v82, v82
	v_rcp_f32_e32 v83, v83
	v_rcp_f32_e32 v180, v180
	v_rcp_f32_e32 v181, v181
	v_mul_f32_e32 v82, v82, v178
	v_mul_f32_e32 v83, v83, v164
	v_mul_f32_e32 v180, v180, v179
	v_mul_f32_e32 v181, v181, v168
	v_mul_f32_e32 v82, v82, v180
	v_mul_f32_e32 v83, v83, v181
	v_lshlrev_b32_e32 v178, 16, v165
	v_and_b32_e32 v165, 0xffff0000, v165
	v_lshlrev_b32_e32 v179, 16, v169
	v_and_b32_e32 v169, 0xffff0000, v169
	v_mul_f32_e32 v84, 0xbfb8aa3b, v84
	v_mul_f32_e32 v85, 0xbfb8aa3b, v85
	v_mul_f32_e32 v180, 0xbfb8aa3b, v179
	v_mul_f32_e32 v181, 0xbfb8aa3b, v169
	v_exp_f32_e32 v84, v84
	v_exp_f32_e32 v85, v85
	v_exp_f32_e32 v180, v180
	v_exp_f32_e32 v181, v181
	v_add_f32_e32 v84, 1.0, v84
	v_add_f32_e32 v85, 1.0, v85
	v_add_f32_e32 v180, 1.0, v180
	v_add_f32_e32 v181, 1.0, v181
	v_rcp_f32_e32 v84, v84
	v_rcp_f32_e32 v85, v85
	v_rcp_f32_e32 v180, v180
	v_rcp_f32_e32 v181, v181
	v_mul_f32_e32 v84, v84, v178
	v_mul_f32_e32 v85, v85, v165
	v_mul_f32_e32 v180, v180, v179
	v_mul_f32_e32 v181, v181, v169
	v_mul_f32_e32 v84, v84, v180
	v_mul_f32_e32 v85, v85, v181
	v_cvt_pk_bf16_f32 v86, v86, v87
	v_cvt_pk_bf16_f32 v87, v88, v89
	v_cvt_pk_bf16_f32 v88, v82, v83
	v_cvt_pk_bf16_f32 v89, v84, v85
	global_store_dwordx4 v[146:147], v[86:89], off offset:256
	s_mov_b64 s[58:59], 0x20000
	v_lshl_add_u64 v[146:147], v[146:147], 0, s[58:59]
	s_mov_b64 s[58:59], 0x28000
	v_lshl_add_u64 v[142:143], v[142:143], 0, s[58:59]
	s_mov_b64 s[58:59], 0x14000
	v_lshl_add_u64 v[144:145], v[144:145], 0, s[58:59]
	global_load_dwordx4 v[162:165], v[142:143], off
	global_load_dwordx4 v[166:169], v[144:145], off
	s_waitcnt vmcnt(6)
	v_lshlrev_b32_e32 v178, 16, v170
	v_and_b32_e32 v170, 0xffff0000, v170
	v_lshlrev_b32_e32 v179, 16, v174
	v_and_b32_e32 v174, 0xffff0000, v174
	v_mul_f32_e32 v78, 0xbfb8aa3b, v78
	v_mul_f32_e32 v79, 0xbfb8aa3b, v79
	v_mul_f32_e32 v180, 0xbfb8aa3b, v179
	v_mul_f32_e32 v181, 0xbfb8aa3b, v174
	v_exp_f32_e32 v78, v78
	v_exp_f32_e32 v79, v79
	v_exp_f32_e32 v180, v180
	v_exp_f32_e32 v181, v181
	v_add_f32_e32 v78, 1.0, v78
	v_add_f32_e32 v79, 1.0, v79
	v_add_f32_e32 v180, 1.0, v180
	v_add_f32_e32 v181, 1.0, v181
	v_rcp_f32_e32 v78, v78
	v_rcp_f32_e32 v79, v79
	v_rcp_f32_e32 v180, v180
	v_rcp_f32_e32 v181, v181
	v_mul_f32_e32 v78, v78, v178
	v_mul_f32_e32 v79, v79, v170
	v_mul_f32_e32 v180, v180, v179
	v_mul_f32_e32 v181, v181, v174
	v_mul_f32_e32 v78, v78, v180
	v_mul_f32_e32 v79, v79, v181
	v_lshlrev_b32_e32 v178, 16, v171
	v_and_b32_e32 v171, 0xffff0000, v171
	v_lshlrev_b32_e32 v179, 16, v175
	v_and_b32_e32 v175, 0xffff0000, v175
	v_mul_f32_e32 v80, 0xbfb8aa3b, v80
	v_mul_f32_e32 v81, 0xbfb8aa3b, v81
	v_mul_f32_e32 v180, 0xbfb8aa3b, v179
	v_mul_f32_e32 v181, 0xbfb8aa3b, v175
	v_exp_f32_e32 v80, v80
	v_exp_f32_e32 v81, v81
	v_exp_f32_e32 v180, v180
	v_exp_f32_e32 v181, v181
	v_add_f32_e32 v80, 1.0, v80
	v_add_f32_e32 v81, 1.0, v81
	v_add_f32_e32 v180, 1.0, v180
	v_add_f32_e32 v181, 1.0, v181
	v_rcp_f32_e32 v80, v80
	v_rcp_f32_e32 v81, v81
	v_rcp_f32_e32 v180, v180
	v_rcp_f32_e32 v181, v181
	v_mul_f32_e32 v80, v80, v178
	v_mul_f32_e32 v81, v81, v171
	v_mul_f32_e32 v180, v180, v179
	v_mul_f32_e32 v181, v181, v175
	v_mul_f32_e32 v80, v80, v180
	v_mul_f32_e32 v81, v81, v181
	v_lshlrev_b32_e32 v178, 16, v172
	v_and_b32_e32 v172, 0xffff0000, v172
	v_lshlrev_b32_e32 v179, 16, v176
	v_and_b32_e32 v176, 0xffff0000, v176
	v_mul_f32_e32 v74, 0xbfb8aa3b, v74
	v_mul_f32_e32 v75, 0xbfb8aa3b, v75
	v_mul_f32_e32 v180, 0xbfb8aa3b, v179
	v_mul_f32_e32 v181, 0xbfb8aa3b, v176
	v_exp_f32_e32 v74, v74
	v_exp_f32_e32 v75, v75
	v_exp_f32_e32 v180, v180
	v_exp_f32_e32 v181, v181
	v_add_f32_e32 v74, 1.0, v74
	v_add_f32_e32 v75, 1.0, v75
	v_add_f32_e32 v180, 1.0, v180
	v_add_f32_e32 v181, 1.0, v181
	v_rcp_f32_e32 v74, v74
	v_rcp_f32_e32 v75, v75
	v_rcp_f32_e32 v180, v180
	v_rcp_f32_e32 v181, v181
	v_mul_f32_e32 v74, v74, v178
	v_mul_f32_e32 v75, v75, v172
	v_mul_f32_e32 v180, v180, v179
	v_mul_f32_e32 v181, v181, v176
	v_mul_f32_e32 v74, v74, v180
	v_mul_f32_e32 v75, v75, v181
	v_lshlrev_b32_e32 v178, 16, v173
	v_and_b32_e32 v173, 0xffff0000, v173
	v_lshlrev_b32_e32 v179, 16, v177
	v_and_b32_e32 v177, 0xffff0000, v177
	v_mul_f32_e32 v76, 0xbfb8aa3b, v76
	v_mul_f32_e32 v77, 0xbfb8aa3b, v77
	v_mul_f32_e32 v180, 0xbfb8aa3b, v179
	v_mul_f32_e32 v181, 0xbfb8aa3b, v177
	v_exp_f32_e32 v76, v76
	v_exp_f32_e32 v77, v77
	v_exp_f32_e32 v180, v180
	v_exp_f32_e32 v181, v181
	v_add_f32_e32 v76, 1.0, v76
	v_add_f32_e32 v77, 1.0, v77
	v_add_f32_e32 v180, 1.0, v180
	v_add_f32_e32 v181, 1.0, v181
	v_rcp_f32_e32 v76, v76
	v_rcp_f32_e32 v77, v77
	v_rcp_f32_e32 v180, v180
	v_rcp_f32_e32 v181, v181
	v_mul_f32_e32 v76, v76, v178
	v_mul_f32_e32 v77, v77, v173
	v_mul_f32_e32 v180, v180, v179
	v_mul_f32_e32 v181, v181, v177
	v_mul_f32_e32 v76, v76, v180
	v_mul_f32_e32 v77, v77, v181
	v_cvt_pk_bf16_f32 v78, v78, v79
	v_cvt_pk_bf16_f32 v79, v80, v81
	v_cvt_pk_bf16_f32 v80, v74, v75
	v_cvt_pk_bf16_f32 v81, v76, v77
	global_store_dwordx4 v[146:147], v[78:81], off
	global_load_dwordx4 v[170:173], v[142:143], off offset:256
	global_load_dwordx4 v[174:177], v[144:145], off offset:256
	s_waitcnt vmcnt(6)
	v_lshlrev_b32_e32 v178, 16, v154
	v_and_b32_e32 v154, 0xffff0000, v154
	v_lshlrev_b32_e32 v179, 16, v158
	v_and_b32_e32 v158, 0xffff0000, v158
	v_mul_f32_e32 v70, 0xbfb8aa3b, v70
	v_mul_f32_e32 v71, 0xbfb8aa3b, v71
	v_mul_f32_e32 v180, 0xbfb8aa3b, v179
	v_mul_f32_e32 v181, 0xbfb8aa3b, v158
	v_exp_f32_e32 v70, v70
	v_exp_f32_e32 v71, v71
	v_exp_f32_e32 v180, v180
	v_exp_f32_e32 v181, v181
	v_add_f32_e32 v70, 1.0, v70
	v_add_f32_e32 v71, 1.0, v71
	v_add_f32_e32 v180, 1.0, v180
	v_add_f32_e32 v181, 1.0, v181
	v_rcp_f32_e32 v70, v70
	v_rcp_f32_e32 v71, v71
	v_rcp_f32_e32 v180, v180
	v_rcp_f32_e32 v181, v181
	v_mul_f32_e32 v70, v70, v178
	v_mul_f32_e32 v71, v71, v154
	v_mul_f32_e32 v180, v180, v179
	v_mul_f32_e32 v181, v181, v158
	v_mul_f32_e32 v70, v70, v180
	v_mul_f32_e32 v71, v71, v181
	v_lshlrev_b32_e32 v178, 16, v155
	v_and_b32_e32 v155, 0xffff0000, v155
	v_lshlrev_b32_e32 v179, 16, v159
	v_and_b32_e32 v159, 0xffff0000, v159
	v_mul_f32_e32 v72, 0xbfb8aa3b, v72
	v_mul_f32_e32 v73, 0xbfb8aa3b, v73
	v_mul_f32_e32 v180, 0xbfb8aa3b, v179
	v_mul_f32_e32 v181, 0xbfb8aa3b, v159
	v_exp_f32_e32 v72, v72
	v_exp_f32_e32 v73, v73
	v_exp_f32_e32 v180, v180
	v_exp_f32_e32 v181, v181
	v_add_f32_e32 v72, 1.0, v72
	v_add_f32_e32 v73, 1.0, v73
	v_add_f32_e32 v180, 1.0, v180
	v_add_f32_e32 v181, 1.0, v181
	v_rcp_f32_e32 v72, v72
	v_rcp_f32_e32 v73, v73
	v_rcp_f32_e32 v180, v180
	v_rcp_f32_e32 v181, v181
	v_mul_f32_e32 v72, v72, v178
	v_mul_f32_e32 v73, v73, v155
	v_mul_f32_e32 v180, v180, v179
	v_mul_f32_e32 v181, v181, v159
	v_mul_f32_e32 v72, v72, v180
	v_mul_f32_e32 v73, v73, v181
	v_lshlrev_b32_e32 v178, 16, v156
	v_and_b32_e32 v156, 0xffff0000, v156
	v_lshlrev_b32_e32 v179, 16, v160
	v_and_b32_e32 v160, 0xffff0000, v160
	v_mul_f32_e32 v66, 0xbfb8aa3b, v66
	v_mul_f32_e32 v67, 0xbfb8aa3b, v67
	v_mul_f32_e32 v180, 0xbfb8aa3b, v179
	v_mul_f32_e32 v181, 0xbfb8aa3b, v160
	v_exp_f32_e32 v66, v66
	v_exp_f32_e32 v67, v67
	v_exp_f32_e32 v180, v180
	v_exp_f32_e32 v181, v181
	v_add_f32_e32 v66, 1.0, v66
	v_add_f32_e32 v67, 1.0, v67
	v_add_f32_e32 v180, 1.0, v180
	v_add_f32_e32 v181, 1.0, v181
	v_rcp_f32_e32 v66, v66
	v_rcp_f32_e32 v67, v67
	v_rcp_f32_e32 v180, v180
	v_rcp_f32_e32 v181, v181
	v_mul_f32_e32 v66, v66, v178
	v_mul_f32_e32 v67, v67, v156
	v_mul_f32_e32 v180, v180, v179
	v_mul_f32_e32 v181, v181, v160
	v_mul_f32_e32 v66, v66, v180
	v_mul_f32_e32 v67, v67, v181
	v_lshlrev_b32_e32 v178, 16, v157
	v_and_b32_e32 v157, 0xffff0000, v157
	v_lshlrev_b32_e32 v179, 16, v161
	v_and_b32_e32 v161, 0xffff0000, v161
	v_mul_f32_e32 v68, 0xbfb8aa3b, v68
	v_mul_f32_e32 v69, 0xbfb8aa3b, v69
	v_mul_f32_e32 v180, 0xbfb8aa3b, v179
	v_mul_f32_e32 v181, 0xbfb8aa3b, v161
	v_exp_f32_e32 v68, v68
	v_exp_f32_e32 v69, v69
	v_exp_f32_e32 v180, v180
	v_exp_f32_e32 v181, v181
	v_add_f32_e32 v68, 1.0, v68
	v_add_f32_e32 v69, 1.0, v69
	v_add_f32_e32 v180, 1.0, v180
	v_add_f32_e32 v181, 1.0, v181
	v_rcp_f32_e32 v68, v68
	v_rcp_f32_e32 v69, v69
	v_rcp_f32_e32 v180, v180
	v_rcp_f32_e32 v181, v181
	v_mul_f32_e32 v68, v68, v178
	v_mul_f32_e32 v69, v69, v157
	v_mul_f32_e32 v180, v180, v179
	v_mul_f32_e32 v181, v181, v161
	v_mul_f32_e32 v68, v68, v180
	v_mul_f32_e32 v69, v69, v181
	v_cvt_pk_bf16_f32 v70, v70, v71
	v_cvt_pk_bf16_f32 v71, v72, v73
	v_cvt_pk_bf16_f32 v72, v66, v67
	v_cvt_pk_bf16_f32 v73, v68, v69
	global_store_dwordx4 v[146:147], v[70:73], off offset:256
	s_mov_b64 s[58:59], 0xa0000
	v_lshl_add_u64 v[146:147], v[146:147], 0, s[58:59]
	s_mov_b64 s[58:59], 0x8000
	v_lshl_add_u64 v[142:143], v[142:143], 0, s[58:59]
	s_mov_b64 s[58:59], 0x4000
	v_lshl_add_u64 v[144:145], v[144:145], 0, s[58:59]
	global_load_dwordx4 v[154:157], v[142:143], off
	global_load_dwordx4 v[158:161], v[144:145], off
	s_waitcnt vmcnt(6)
	v_lshlrev_b32_e32 v178, 16, v162
	v_and_b32_e32 v162, 0xffff0000, v162
	v_lshlrev_b32_e32 v179, 16, v166
	v_and_b32_e32 v166, 0xffff0000, v166
	v_mul_f32_e32 v62, 0xbfb8aa3b, v62
	v_mul_f32_e32 v63, 0xbfb8aa3b, v63
	v_mul_f32_e32 v180, 0xbfb8aa3b, v179
	v_mul_f32_e32 v181, 0xbfb8aa3b, v166
	v_exp_f32_e32 v62, v62
	v_exp_f32_e32 v63, v63
	v_exp_f32_e32 v180, v180
	v_exp_f32_e32 v181, v181
	v_add_f32_e32 v62, 1.0, v62
	v_add_f32_e32 v63, 1.0, v63
	v_add_f32_e32 v180, 1.0, v180
	v_add_f32_e32 v181, 1.0, v181
	v_rcp_f32_e32 v62, v62
	v_rcp_f32_e32 v63, v63
	v_rcp_f32_e32 v180, v180
	v_rcp_f32_e32 v181, v181
	v_mul_f32_e32 v62, v62, v178
	v_mul_f32_e32 v63, v63, v162
	v_mul_f32_e32 v180, v180, v179
	v_mul_f32_e32 v181, v181, v166
	v_mul_f32_e32 v62, v62, v180
	v_mul_f32_e32 v63, v63, v181
	v_lshlrev_b32_e32 v178, 16, v163
	v_and_b32_e32 v163, 0xffff0000, v163
	v_lshlrev_b32_e32 v179, 16, v167
	v_and_b32_e32 v167, 0xffff0000, v167
	v_mul_f32_e32 v64, 0xbfb8aa3b, v64
	v_mul_f32_e32 v65, 0xbfb8aa3b, v65
	v_mul_f32_e32 v180, 0xbfb8aa3b, v179
	v_mul_f32_e32 v181, 0xbfb8aa3b, v167
	v_exp_f32_e32 v64, v64
	v_exp_f32_e32 v65, v65
	v_exp_f32_e32 v180, v180
	v_exp_f32_e32 v181, v181
	v_add_f32_e32 v64, 1.0, v64
	v_add_f32_e32 v65, 1.0, v65
	v_add_f32_e32 v180, 1.0, v180
	v_add_f32_e32 v181, 1.0, v181
	v_rcp_f32_e32 v64, v64
	v_rcp_f32_e32 v65, v65
	v_rcp_f32_e32 v180, v180
	v_rcp_f32_e32 v181, v181
	v_mul_f32_e32 v64, v64, v178
	v_mul_f32_e32 v65, v65, v163
	v_mul_f32_e32 v180, v180, v179
	v_mul_f32_e32 v181, v181, v167
	v_mul_f32_e32 v64, v64, v180
	v_mul_f32_e32 v65, v65, v181
	v_lshlrev_b32_e32 v178, 16, v164
	v_and_b32_e32 v164, 0xffff0000, v164
	v_lshlrev_b32_e32 v179, 16, v168
	v_and_b32_e32 v168, 0xffff0000, v168
	v_mul_f32_e32 v58, 0xbfb8aa3b, v58
	v_mul_f32_e32 v59, 0xbfb8aa3b, v59
	v_mul_f32_e32 v180, 0xbfb8aa3b, v179
	v_mul_f32_e32 v181, 0xbfb8aa3b, v168
	v_exp_f32_e32 v58, v58
	v_exp_f32_e32 v59, v59
	v_exp_f32_e32 v180, v180
	v_exp_f32_e32 v181, v181
	v_add_f32_e32 v58, 1.0, v58
	v_add_f32_e32 v59, 1.0, v59
	v_add_f32_e32 v180, 1.0, v180
	v_add_f32_e32 v181, 1.0, v181
	v_rcp_f32_e32 v58, v58
	v_rcp_f32_e32 v59, v59
	v_rcp_f32_e32 v180, v180
	v_rcp_f32_e32 v181, v181
	v_mul_f32_e32 v58, v58, v178
	v_mul_f32_e32 v59, v59, v164
	v_mul_f32_e32 v180, v180, v179
	v_mul_f32_e32 v181, v181, v168
	v_mul_f32_e32 v58, v58, v180
	v_mul_f32_e32 v59, v59, v181
	v_lshlrev_b32_e32 v178, 16, v165
	v_and_b32_e32 v165, 0xffff0000, v165
	v_lshlrev_b32_e32 v179, 16, v169
	v_and_b32_e32 v169, 0xffff0000, v169
	v_mul_f32_e32 v60, 0xbfb8aa3b, v60
	v_mul_f32_e32 v61, 0xbfb8aa3b, v61
	v_mul_f32_e32 v180, 0xbfb8aa3b, v179
	v_mul_f32_e32 v181, 0xbfb8aa3b, v169
	v_exp_f32_e32 v60, v60
	v_exp_f32_e32 v61, v61
	v_exp_f32_e32 v180, v180
	v_exp_f32_e32 v181, v181
	v_add_f32_e32 v60, 1.0, v60
	v_add_f32_e32 v61, 1.0, v61
	v_add_f32_e32 v180, 1.0, v180
	v_add_f32_e32 v181, 1.0, v181
	v_rcp_f32_e32 v60, v60
	v_rcp_f32_e32 v61, v61
	v_rcp_f32_e32 v180, v180
	v_rcp_f32_e32 v181, v181
	v_mul_f32_e32 v60, v60, v178
	v_mul_f32_e32 v61, v61, v165
	v_mul_f32_e32 v180, v180, v179
	v_mul_f32_e32 v181, v181, v169
	v_mul_f32_e32 v60, v60, v180
	v_mul_f32_e32 v61, v61, v181
	v_cvt_pk_bf16_f32 v62, v62, v63
	v_cvt_pk_bf16_f32 v63, v64, v65
	v_cvt_pk_bf16_f32 v64, v58, v59
	v_cvt_pk_bf16_f32 v65, v60, v61
	global_store_dwordx4 v[146:147], v[62:65], off
	global_load_dwordx4 v[162:165], v[142:143], off offset:256
	global_load_dwordx4 v[166:169], v[144:145], off offset:256
	s_waitcnt vmcnt(6)
	v_lshlrev_b32_e32 v178, 16, v170
	v_and_b32_e32 v170, 0xffff0000, v170
	v_lshlrev_b32_e32 v179, 16, v174
	v_and_b32_e32 v174, 0xffff0000, v174
	v_mul_f32_e32 v54, 0xbfb8aa3b, v54
	v_mul_f32_e32 v55, 0xbfb8aa3b, v55
	v_mul_f32_e32 v180, 0xbfb8aa3b, v179
	v_mul_f32_e32 v181, 0xbfb8aa3b, v174
	v_exp_f32_e32 v54, v54
	v_exp_f32_e32 v55, v55
	v_exp_f32_e32 v180, v180
	v_exp_f32_e32 v181, v181
	v_add_f32_e32 v54, 1.0, v54
	v_add_f32_e32 v55, 1.0, v55
	v_add_f32_e32 v180, 1.0, v180
	v_add_f32_e32 v181, 1.0, v181
	v_rcp_f32_e32 v54, v54
	v_rcp_f32_e32 v55, v55
	v_rcp_f32_e32 v180, v180
	v_rcp_f32_e32 v181, v181
	v_mul_f32_e32 v54, v54, v178
	v_mul_f32_e32 v55, v55, v170
	v_mul_f32_e32 v180, v180, v179
	v_mul_f32_e32 v181, v181, v174
	v_mul_f32_e32 v54, v54, v180
	v_mul_f32_e32 v55, v55, v181
	v_lshlrev_b32_e32 v178, 16, v171
	v_and_b32_e32 v171, 0xffff0000, v171
	v_lshlrev_b32_e32 v179, 16, v175
	v_and_b32_e32 v175, 0xffff0000, v175
	v_mul_f32_e32 v56, 0xbfb8aa3b, v56
	v_mul_f32_e32 v57, 0xbfb8aa3b, v57
	v_mul_f32_e32 v180, 0xbfb8aa3b, v179
	v_mul_f32_e32 v181, 0xbfb8aa3b, v175
	v_exp_f32_e32 v56, v56
	v_exp_f32_e32 v57, v57
	v_exp_f32_e32 v180, v180
	v_exp_f32_e32 v181, v181
	v_add_f32_e32 v56, 1.0, v56
	v_add_f32_e32 v57, 1.0, v57
	v_add_f32_e32 v180, 1.0, v180
	v_add_f32_e32 v181, 1.0, v181
	v_rcp_f32_e32 v56, v56
	v_rcp_f32_e32 v57, v57
	v_rcp_f32_e32 v180, v180
	v_rcp_f32_e32 v181, v181
	v_mul_f32_e32 v56, v56, v178
	v_mul_f32_e32 v57, v57, v171
	v_mul_f32_e32 v180, v180, v179
	v_mul_f32_e32 v181, v181, v175
	v_mul_f32_e32 v56, v56, v180
	v_mul_f32_e32 v57, v57, v181
	v_lshlrev_b32_e32 v178, 16, v172
	v_and_b32_e32 v172, 0xffff0000, v172
	v_lshlrev_b32_e32 v179, 16, v176
	v_and_b32_e32 v176, 0xffff0000, v176
	v_mul_f32_e32 v50, 0xbfb8aa3b, v50
	v_mul_f32_e32 v51, 0xbfb8aa3b, v51
	v_mul_f32_e32 v180, 0xbfb8aa3b, v179
	v_mul_f32_e32 v181, 0xbfb8aa3b, v176
	v_exp_f32_e32 v50, v50
	v_exp_f32_e32 v51, v51
	v_exp_f32_e32 v180, v180
	v_exp_f32_e32 v181, v181
	v_add_f32_e32 v50, 1.0, v50
	v_add_f32_e32 v51, 1.0, v51
	v_add_f32_e32 v180, 1.0, v180
	v_add_f32_e32 v181, 1.0, v181
	v_rcp_f32_e32 v50, v50
	v_rcp_f32_e32 v51, v51
	v_rcp_f32_e32 v180, v180
	v_rcp_f32_e32 v181, v181
	v_mul_f32_e32 v50, v50, v178
	v_mul_f32_e32 v51, v51, v172
	v_mul_f32_e32 v180, v180, v179
	v_mul_f32_e32 v181, v181, v176
	v_mul_f32_e32 v50, v50, v180
	v_mul_f32_e32 v51, v51, v181
	v_lshlrev_b32_e32 v178, 16, v173
	v_and_b32_e32 v173, 0xffff0000, v173
	v_lshlrev_b32_e32 v179, 16, v177
	v_and_b32_e32 v177, 0xffff0000, v177
	v_mul_f32_e32 v52, 0xbfb8aa3b, v52
	v_mul_f32_e32 v53, 0xbfb8aa3b, v53
	v_mul_f32_e32 v180, 0xbfb8aa3b, v179
	v_mul_f32_e32 v181, 0xbfb8aa3b, v177
	v_exp_f32_e32 v52, v52
	v_exp_f32_e32 v53, v53
	v_exp_f32_e32 v180, v180
	v_exp_f32_e32 v181, v181
	v_add_f32_e32 v52, 1.0, v52
	v_add_f32_e32 v53, 1.0, v53
	v_add_f32_e32 v180, 1.0, v180
	v_add_f32_e32 v181, 1.0, v181
	v_rcp_f32_e32 v52, v52
	v_rcp_f32_e32 v53, v53
	v_rcp_f32_e32 v180, v180
	v_rcp_f32_e32 v181, v181
	v_mul_f32_e32 v52, v52, v178
	v_mul_f32_e32 v53, v53, v173
	v_mul_f32_e32 v180, v180, v179
	v_mul_f32_e32 v181, v181, v177
	v_mul_f32_e32 v52, v52, v180
	v_mul_f32_e32 v53, v53, v181
	v_cvt_pk_bf16_f32 v54, v54, v55
	v_cvt_pk_bf16_f32 v55, v56, v57
	v_cvt_pk_bf16_f32 v56, v50, v51
	v_cvt_pk_bf16_f32 v57, v52, v53
	global_store_dwordx4 v[146:147], v[54:57], off offset:256
	s_mov_b64 s[58:59], 0x20000
	v_lshl_add_u64 v[146:147], v[146:147], 0, s[58:59]
	s_mov_b64 s[58:59], 0x8000
	v_lshl_add_u64 v[142:143], v[142:143], 0, s[58:59]
	s_mov_b64 s[58:59], 0x4000
	v_lshl_add_u64 v[144:145], v[144:145], 0, s[58:59]
	global_load_dwordx4 v[170:173], v[142:143], off
	global_load_dwordx4 v[174:177], v[144:145], off
	s_waitcnt vmcnt(6)
	v_lshlrev_b32_e32 v178, 16, v154
	v_and_b32_e32 v154, 0xffff0000, v154
	v_lshlrev_b32_e32 v179, 16, v158
	v_and_b32_e32 v158, 0xffff0000, v158
	v_mul_f32_e32 v46, 0xbfb8aa3b, v46
	v_mul_f32_e32 v47, 0xbfb8aa3b, v47
	v_mul_f32_e32 v180, 0xbfb8aa3b, v179
	v_mul_f32_e32 v181, 0xbfb8aa3b, v158
	v_exp_f32_e32 v46, v46
	v_exp_f32_e32 v47, v47
	v_exp_f32_e32 v180, v180
	v_exp_f32_e32 v181, v181
	v_add_f32_e32 v46, 1.0, v46
	v_add_f32_e32 v47, 1.0, v47
	v_add_f32_e32 v180, 1.0, v180
	v_add_f32_e32 v181, 1.0, v181
	v_rcp_f32_e32 v46, v46
	v_rcp_f32_e32 v47, v47
	v_rcp_f32_e32 v180, v180
	v_rcp_f32_e32 v181, v181
	v_mul_f32_e32 v46, v46, v178
	v_mul_f32_e32 v47, v47, v154
	v_mul_f32_e32 v180, v180, v179
	v_mul_f32_e32 v181, v181, v158
	v_mul_f32_e32 v46, v46, v180
	v_mul_f32_e32 v47, v47, v181
	v_lshlrev_b32_e32 v178, 16, v155
	v_and_b32_e32 v155, 0xffff0000, v155
	v_lshlrev_b32_e32 v179, 16, v159
	v_and_b32_e32 v159, 0xffff0000, v159
	v_mul_f32_e32 v48, 0xbfb8aa3b, v48
	v_mul_f32_e32 v49, 0xbfb8aa3b, v49
	v_mul_f32_e32 v180, 0xbfb8aa3b, v179
	v_mul_f32_e32 v181, 0xbfb8aa3b, v159
	v_exp_f32_e32 v48, v48
	v_exp_f32_e32 v49, v49
	v_exp_f32_e32 v180, v180
	v_exp_f32_e32 v181, v181
	v_add_f32_e32 v48, 1.0, v48
	v_add_f32_e32 v49, 1.0, v49
	v_add_f32_e32 v180, 1.0, v180
	v_add_f32_e32 v181, 1.0, v181
	v_rcp_f32_e32 v48, v48
	v_rcp_f32_e32 v49, v49
	v_rcp_f32_e32 v180, v180
	v_rcp_f32_e32 v181, v181
	v_mul_f32_e32 v48, v48, v178
	v_mul_f32_e32 v49, v49, v155
	v_mul_f32_e32 v180, v180, v179
	v_mul_f32_e32 v181, v181, v159
	v_mul_f32_e32 v48, v48, v180
	v_mul_f32_e32 v49, v49, v181
	v_lshlrev_b32_e32 v178, 16, v156
	v_and_b32_e32 v156, 0xffff0000, v156
	v_lshlrev_b32_e32 v179, 16, v160
	v_and_b32_e32 v160, 0xffff0000, v160
	v_mul_f32_e32 v42, 0xbfb8aa3b, v42
	v_mul_f32_e32 v43, 0xbfb8aa3b, v43
	v_mul_f32_e32 v180, 0xbfb8aa3b, v179
	v_mul_f32_e32 v181, 0xbfb8aa3b, v160
	v_exp_f32_e32 v42, v42
	v_exp_f32_e32 v43, v43
	v_exp_f32_e32 v180, v180
	v_exp_f32_e32 v181, v181
	v_add_f32_e32 v42, 1.0, v42
	v_add_f32_e32 v43, 1.0, v43
	v_add_f32_e32 v180, 1.0, v180
	v_add_f32_e32 v181, 1.0, v181
	v_rcp_f32_e32 v42, v42
	v_rcp_f32_e32 v43, v43
	v_rcp_f32_e32 v180, v180
	v_rcp_f32_e32 v181, v181
	v_mul_f32_e32 v42, v42, v178
	v_mul_f32_e32 v43, v43, v156
	v_mul_f32_e32 v180, v180, v179
	v_mul_f32_e32 v181, v181, v160
	v_mul_f32_e32 v42, v42, v180
	v_mul_f32_e32 v43, v43, v181
	v_lshlrev_b32_e32 v178, 16, v157
	v_and_b32_e32 v157, 0xffff0000, v157
	v_lshlrev_b32_e32 v179, 16, v161
	v_and_b32_e32 v161, 0xffff0000, v161
	v_mul_f32_e32 v44, 0xbfb8aa3b, v44
	v_mul_f32_e32 v45, 0xbfb8aa3b, v45
	v_mul_f32_e32 v180, 0xbfb8aa3b, v179
	v_mul_f32_e32 v181, 0xbfb8aa3b, v161
	v_exp_f32_e32 v44, v44
	v_exp_f32_e32 v45, v45
	v_exp_f32_e32 v180, v180
	v_exp_f32_e32 v181, v181
	v_add_f32_e32 v44, 1.0, v44
	v_add_f32_e32 v45, 1.0, v45
	v_add_f32_e32 v180, 1.0, v180
	v_add_f32_e32 v181, 1.0, v181
	v_rcp_f32_e32 v44, v44
	v_rcp_f32_e32 v45, v45
	v_rcp_f32_e32 v180, v180
	v_rcp_f32_e32 v181, v181
	v_mul_f32_e32 v44, v44, v178
	v_mul_f32_e32 v45, v45, v157
	v_mul_f32_e32 v180, v180, v179
	v_mul_f32_e32 v181, v181, v161
	v_mul_f32_e32 v44, v44, v180
	v_mul_f32_e32 v45, v45, v181
	v_cvt_pk_bf16_f32 v46, v46, v47
	v_cvt_pk_bf16_f32 v47, v48, v49
	v_cvt_pk_bf16_f32 v48, v42, v43
	v_cvt_pk_bf16_f32 v49, v44, v45
	global_store_dwordx4 v[146:147], v[46:49], off
	global_load_dwordx4 v[154:157], v[142:143], off offset:256
	global_load_dwordx4 v[158:161], v[144:145], off offset:256
	s_waitcnt vmcnt(6)
	v_lshlrev_b32_e32 v178, 16, v162
	v_and_b32_e32 v162, 0xffff0000, v162
	v_lshlrev_b32_e32 v179, 16, v166
	v_and_b32_e32 v166, 0xffff0000, v166
	v_mul_f32_e32 v38, 0xbfb8aa3b, v38
	v_mul_f32_e32 v39, 0xbfb8aa3b, v39
	v_mul_f32_e32 v180, 0xbfb8aa3b, v179
	v_mul_f32_e32 v181, 0xbfb8aa3b, v166
	v_exp_f32_e32 v38, v38
	v_exp_f32_e32 v39, v39
	v_exp_f32_e32 v180, v180
	v_exp_f32_e32 v181, v181
	v_add_f32_e32 v38, 1.0, v38
	v_add_f32_e32 v39, 1.0, v39
	v_add_f32_e32 v180, 1.0, v180
	v_add_f32_e32 v181, 1.0, v181
	v_rcp_f32_e32 v38, v38
	v_rcp_f32_e32 v39, v39
	v_rcp_f32_e32 v180, v180
	v_rcp_f32_e32 v181, v181
	v_mul_f32_e32 v38, v38, v178
	v_mul_f32_e32 v39, v39, v162
	v_mul_f32_e32 v180, v180, v179
	v_mul_f32_e32 v181, v181, v166
	v_mul_f32_e32 v38, v38, v180
	v_mul_f32_e32 v39, v39, v181
	v_lshlrev_b32_e32 v178, 16, v163
	v_and_b32_e32 v163, 0xffff0000, v163
	v_lshlrev_b32_e32 v179, 16, v167
	v_and_b32_e32 v167, 0xffff0000, v167
	v_mul_f32_e32 v40, 0xbfb8aa3b, v40
	v_mul_f32_e32 v41, 0xbfb8aa3b, v41
	v_mul_f32_e32 v180, 0xbfb8aa3b, v179
	v_mul_f32_e32 v181, 0xbfb8aa3b, v167
	v_exp_f32_e32 v40, v40
	v_exp_f32_e32 v41, v41
	v_exp_f32_e32 v180, v180
	v_exp_f32_e32 v181, v181
	v_add_f32_e32 v40, 1.0, v40
	v_add_f32_e32 v41, 1.0, v41
	v_add_f32_e32 v180, 1.0, v180
	v_add_f32_e32 v181, 1.0, v181
	v_rcp_f32_e32 v40, v40
	v_rcp_f32_e32 v41, v41
	v_rcp_f32_e32 v180, v180
	v_rcp_f32_e32 v181, v181
	v_mul_f32_e32 v40, v40, v178
	v_mul_f32_e32 v41, v41, v163
	v_mul_f32_e32 v180, v180, v179
	v_mul_f32_e32 v181, v181, v167
	v_mul_f32_e32 v40, v40, v180
	v_mul_f32_e32 v41, v41, v181
	v_lshlrev_b32_e32 v178, 16, v164
	v_and_b32_e32 v164, 0xffff0000, v164
	v_lshlrev_b32_e32 v179, 16, v168
	v_and_b32_e32 v168, 0xffff0000, v168
	v_mul_f32_e32 v34, 0xbfb8aa3b, v34
	v_mul_f32_e32 v35, 0xbfb8aa3b, v35
	v_mul_f32_e32 v180, 0xbfb8aa3b, v179
	v_mul_f32_e32 v181, 0xbfb8aa3b, v168
	v_exp_f32_e32 v34, v34
	v_exp_f32_e32 v35, v35
	v_exp_f32_e32 v180, v180
	v_exp_f32_e32 v181, v181
	v_add_f32_e32 v34, 1.0, v34
	v_add_f32_e32 v35, 1.0, v35
	v_add_f32_e32 v180, 1.0, v180
	v_add_f32_e32 v181, 1.0, v181
	v_rcp_f32_e32 v34, v34
	v_rcp_f32_e32 v35, v35
	v_rcp_f32_e32 v180, v180
	v_rcp_f32_e32 v181, v181
	v_mul_f32_e32 v34, v34, v178
	v_mul_f32_e32 v35, v35, v164
	v_mul_f32_e32 v180, v180, v179
	v_mul_f32_e32 v181, v181, v168
	v_mul_f32_e32 v34, v34, v180
	v_mul_f32_e32 v35, v35, v181
	v_lshlrev_b32_e32 v178, 16, v165
	v_and_b32_e32 v165, 0xffff0000, v165
	v_lshlrev_b32_e32 v179, 16, v169
	v_and_b32_e32 v169, 0xffff0000, v169
	v_mul_f32_e32 v36, 0xbfb8aa3b, v36
	v_mul_f32_e32 v37, 0xbfb8aa3b, v37
	v_mul_f32_e32 v180, 0xbfb8aa3b, v179
	v_mul_f32_e32 v181, 0xbfb8aa3b, v169
	v_exp_f32_e32 v36, v36
	v_exp_f32_e32 v37, v37
	v_exp_f32_e32 v180, v180
	v_exp_f32_e32 v181, v181
	v_add_f32_e32 v36, 1.0, v36
	v_add_f32_e32 v37, 1.0, v37
	v_add_f32_e32 v180, 1.0, v180
	v_add_f32_e32 v181, 1.0, v181
	v_rcp_f32_e32 v36, v36
	v_rcp_f32_e32 v37, v37
	v_rcp_f32_e32 v180, v180
	v_rcp_f32_e32 v181, v181
	v_mul_f32_e32 v36, v36, v178
	v_mul_f32_e32 v37, v37, v165
	v_mul_f32_e32 v180, v180, v179
	v_mul_f32_e32 v181, v181, v169
	v_mul_f32_e32 v36, v36, v180
	v_mul_f32_e32 v37, v37, v181
	v_cvt_pk_bf16_f32 v38, v38, v39
	v_cvt_pk_bf16_f32 v39, v40, v41
	v_cvt_pk_bf16_f32 v40, v34, v35
	v_cvt_pk_bf16_f32 v41, v36, v37
	global_store_dwordx4 v[146:147], v[38:41], off offset:256
	s_mov_b64 s[58:59], 0x20000
	v_lshl_add_u64 v[146:147], v[146:147], 0, s[58:59]
	s_mov_b64 s[58:59], 0x8000
	v_lshl_add_u64 v[142:143], v[142:143], 0, s[58:59]
	s_mov_b64 s[58:59], 0x4000
	v_lshl_add_u64 v[144:145], v[144:145], 0, s[58:59]
	global_load_dwordx4 v[162:165], v[142:143], off
	global_load_dwordx4 v[166:169], v[144:145], off
	s_waitcnt vmcnt(6)
	v_lshlrev_b32_e32 v178, 16, v170
	v_and_b32_e32 v170, 0xffff0000, v170
	v_lshlrev_b32_e32 v179, 16, v174
	v_and_b32_e32 v174, 0xffff0000, v174
	v_mul_f32_e32 v30, 0xbfb8aa3b, v30
	v_mul_f32_e32 v31, 0xbfb8aa3b, v31
	v_mul_f32_e32 v180, 0xbfb8aa3b, v179
	v_mul_f32_e32 v181, 0xbfb8aa3b, v174
	v_exp_f32_e32 v30, v30
	v_exp_f32_e32 v31, v31
	v_exp_f32_e32 v180, v180
	v_exp_f32_e32 v181, v181
	v_add_f32_e32 v30, 1.0, v30
	v_add_f32_e32 v31, 1.0, v31
	v_add_f32_e32 v180, 1.0, v180
	v_add_f32_e32 v181, 1.0, v181
	v_rcp_f32_e32 v30, v30
	v_rcp_f32_e32 v31, v31
	v_rcp_f32_e32 v180, v180
	v_rcp_f32_e32 v181, v181
	v_mul_f32_e32 v30, v30, v178
	v_mul_f32_e32 v31, v31, v170
	v_mul_f32_e32 v180, v180, v179
	v_mul_f32_e32 v181, v181, v174
	v_mul_f32_e32 v30, v30, v180
	v_mul_f32_e32 v31, v31, v181
	v_lshlrev_b32_e32 v178, 16, v171
	v_and_b32_e32 v171, 0xffff0000, v171
	v_lshlrev_b32_e32 v179, 16, v175
	v_and_b32_e32 v175, 0xffff0000, v175
	v_mul_f32_e32 v32, 0xbfb8aa3b, v32
	v_mul_f32_e32 v33, 0xbfb8aa3b, v33
	v_mul_f32_e32 v180, 0xbfb8aa3b, v179
	v_mul_f32_e32 v181, 0xbfb8aa3b, v175
	v_exp_f32_e32 v32, v32
	v_exp_f32_e32 v33, v33
	v_exp_f32_e32 v180, v180
	v_exp_f32_e32 v181, v181
	v_add_f32_e32 v32, 1.0, v32
	v_add_f32_e32 v33, 1.0, v33
	v_add_f32_e32 v180, 1.0, v180
	v_add_f32_e32 v181, 1.0, v181
	v_rcp_f32_e32 v32, v32
	v_rcp_f32_e32 v33, v33
	v_rcp_f32_e32 v180, v180
	v_rcp_f32_e32 v181, v181
	v_mul_f32_e32 v32, v32, v178
	v_mul_f32_e32 v33, v33, v171
	v_mul_f32_e32 v180, v180, v179
	v_mul_f32_e32 v181, v181, v175
	v_mul_f32_e32 v32, v32, v180
	v_mul_f32_e32 v33, v33, v181
	v_lshlrev_b32_e32 v178, 16, v172
	v_and_b32_e32 v172, 0xffff0000, v172
	v_lshlrev_b32_e32 v179, 16, v176
	v_and_b32_e32 v176, 0xffff0000, v176
	v_mul_f32_e32 v26, 0xbfb8aa3b, v26
	v_mul_f32_e32 v27, 0xbfb8aa3b, v27
	v_mul_f32_e32 v180, 0xbfb8aa3b, v179
	v_mul_f32_e32 v181, 0xbfb8aa3b, v176
	v_exp_f32_e32 v26, v26
	v_exp_f32_e32 v27, v27
	v_exp_f32_e32 v180, v180
	v_exp_f32_e32 v181, v181
	v_add_f32_e32 v26, 1.0, v26
	v_add_f32_e32 v27, 1.0, v27
	v_add_f32_e32 v180, 1.0, v180
	v_add_f32_e32 v181, 1.0, v181
	v_rcp_f32_e32 v26, v26
	v_rcp_f32_e32 v27, v27
	v_rcp_f32_e32 v180, v180
	v_rcp_f32_e32 v181, v181
	v_mul_f32_e32 v26, v26, v178
	v_mul_f32_e32 v27, v27, v172
	v_mul_f32_e32 v180, v180, v179
	v_mul_f32_e32 v181, v181, v176
	v_mul_f32_e32 v26, v26, v180
	v_mul_f32_e32 v27, v27, v181
	v_lshlrev_b32_e32 v178, 16, v173
	v_and_b32_e32 v173, 0xffff0000, v173
	v_lshlrev_b32_e32 v179, 16, v177
	v_and_b32_e32 v177, 0xffff0000, v177
	v_mul_f32_e32 v28, 0xbfb8aa3b, v28
	v_mul_f32_e32 v29, 0xbfb8aa3b, v29
	v_mul_f32_e32 v180, 0xbfb8aa3b, v179
	v_mul_f32_e32 v181, 0xbfb8aa3b, v177
	v_exp_f32_e32 v28, v28
	v_exp_f32_e32 v29, v29
	v_exp_f32_e32 v180, v180
	v_exp_f32_e32 v181, v181
	v_add_f32_e32 v28, 1.0, v28
	v_add_f32_e32 v29, 1.0, v29
	v_add_f32_e32 v180, 1.0, v180
	v_add_f32_e32 v181, 1.0, v181
	v_rcp_f32_e32 v28, v28
	v_rcp_f32_e32 v29, v29
	v_rcp_f32_e32 v180, v180
	v_rcp_f32_e32 v181, v181
	v_mul_f32_e32 v28, v28, v178
	v_mul_f32_e32 v29, v29, v173
	v_mul_f32_e32 v180, v180, v179
	v_mul_f32_e32 v181, v181, v177
	v_mul_f32_e32 v28, v28, v180
	v_mul_f32_e32 v29, v29, v181
	v_cvt_pk_bf16_f32 v30, v30, v31
	v_cvt_pk_bf16_f32 v31, v32, v33
	v_cvt_pk_bf16_f32 v32, v26, v27
	v_cvt_pk_bf16_f32 v33, v28, v29
	global_store_dwordx4 v[146:147], v[30:33], off
	global_load_dwordx4 v[170:173], v[142:143], off offset:256
	global_load_dwordx4 v[174:177], v[144:145], off offset:256
	s_waitcnt vmcnt(6)
	v_lshlrev_b32_e32 v178, 16, v154
	v_and_b32_e32 v154, 0xffff0000, v154
	v_lshlrev_b32_e32 v179, 16, v158
	v_and_b32_e32 v158, 0xffff0000, v158
	v_mul_f32_e32 v22, 0xbfb8aa3b, v22
	v_mul_f32_e32 v23, 0xbfb8aa3b, v23
	v_mul_f32_e32 v180, 0xbfb8aa3b, v179
	v_mul_f32_e32 v181, 0xbfb8aa3b, v158
	v_exp_f32_e32 v22, v22
	v_exp_f32_e32 v23, v23
	v_exp_f32_e32 v180, v180
	v_exp_f32_e32 v181, v181
	v_add_f32_e32 v22, 1.0, v22
	v_add_f32_e32 v23, 1.0, v23
	v_add_f32_e32 v180, 1.0, v180
	v_add_f32_e32 v181, 1.0, v181
	v_rcp_f32_e32 v22, v22
	v_rcp_f32_e32 v23, v23
	v_rcp_f32_e32 v180, v180
	v_rcp_f32_e32 v181, v181
	v_mul_f32_e32 v22, v22, v178
	v_mul_f32_e32 v23, v23, v154
	v_mul_f32_e32 v180, v180, v179
	v_mul_f32_e32 v181, v181, v158
	v_mul_f32_e32 v22, v22, v180
	v_mul_f32_e32 v23, v23, v181
	v_lshlrev_b32_e32 v178, 16, v155
	v_and_b32_e32 v155, 0xffff0000, v155
	v_lshlrev_b32_e32 v179, 16, v159
	v_and_b32_e32 v159, 0xffff0000, v159
	v_mul_f32_e32 v24, 0xbfb8aa3b, v24
	v_mul_f32_e32 v25, 0xbfb8aa3b, v25
	v_mul_f32_e32 v180, 0xbfb8aa3b, v179
	v_mul_f32_e32 v181, 0xbfb8aa3b, v159
	v_exp_f32_e32 v24, v24
	v_exp_f32_e32 v25, v25
	v_exp_f32_e32 v180, v180
	v_exp_f32_e32 v181, v181
	v_add_f32_e32 v24, 1.0, v24
	v_add_f32_e32 v25, 1.0, v25
	v_add_f32_e32 v180, 1.0, v180
	v_add_f32_e32 v181, 1.0, v181
	v_rcp_f32_e32 v24, v24
	v_rcp_f32_e32 v25, v25
	v_rcp_f32_e32 v180, v180
	v_rcp_f32_e32 v181, v181
	v_mul_f32_e32 v24, v24, v178
	v_mul_f32_e32 v25, v25, v155
	v_mul_f32_e32 v180, v180, v179
	v_mul_f32_e32 v181, v181, v159
	v_mul_f32_e32 v24, v24, v180
	v_mul_f32_e32 v25, v25, v181
	v_lshlrev_b32_e32 v178, 16, v156
	v_and_b32_e32 v156, 0xffff0000, v156
	v_lshlrev_b32_e32 v179, 16, v160
	v_and_b32_e32 v160, 0xffff0000, v160
	v_mul_f32_e32 v18, 0xbfb8aa3b, v18
	v_mul_f32_e32 v19, 0xbfb8aa3b, v19
	v_mul_f32_e32 v180, 0xbfb8aa3b, v179
	v_mul_f32_e32 v181, 0xbfb8aa3b, v160
	v_exp_f32_e32 v18, v18
	v_exp_f32_e32 v19, v19
	v_exp_f32_e32 v180, v180
	v_exp_f32_e32 v181, v181
	v_add_f32_e32 v18, 1.0, v18
	v_add_f32_e32 v19, 1.0, v19
	v_add_f32_e32 v180, 1.0, v180
	v_add_f32_e32 v181, 1.0, v181
	v_rcp_f32_e32 v18, v18
	v_rcp_f32_e32 v19, v19
	v_rcp_f32_e32 v180, v180
	v_rcp_f32_e32 v181, v181
	v_mul_f32_e32 v18, v18, v178
	v_mul_f32_e32 v19, v19, v156
	v_mul_f32_e32 v180, v180, v179
	v_mul_f32_e32 v181, v181, v160
	v_mul_f32_e32 v18, v18, v180
	v_mul_f32_e32 v19, v19, v181
	v_lshlrev_b32_e32 v178, 16, v157
	v_and_b32_e32 v157, 0xffff0000, v157
	v_lshlrev_b32_e32 v179, 16, v161
	v_and_b32_e32 v161, 0xffff0000, v161
	v_mul_f32_e32 v20, 0xbfb8aa3b, v20
	v_mul_f32_e32 v21, 0xbfb8aa3b, v21
	v_mul_f32_e32 v180, 0xbfb8aa3b, v179
	v_mul_f32_e32 v181, 0xbfb8aa3b, v161
	v_exp_f32_e32 v20, v20
	v_exp_f32_e32 v21, v21
	v_exp_f32_e32 v180, v180
	v_exp_f32_e32 v181, v181
	v_add_f32_e32 v20, 1.0, v20
	v_add_f32_e32 v21, 1.0, v21
	v_add_f32_e32 v180, 1.0, v180
	v_add_f32_e32 v181, 1.0, v181
	v_rcp_f32_e32 v20, v20
	v_rcp_f32_e32 v21, v21
	v_rcp_f32_e32 v180, v180
	v_rcp_f32_e32 v181, v181
	v_mul_f32_e32 v20, v20, v178
	v_mul_f32_e32 v21, v21, v157
	v_mul_f32_e32 v180, v180, v179
	v_mul_f32_e32 v181, v181, v161
	v_mul_f32_e32 v20, v20, v180
	v_mul_f32_e32 v21, v21, v181
	v_cvt_pk_bf16_f32 v22, v22, v23
	v_cvt_pk_bf16_f32 v23, v24, v25
	v_cvt_pk_bf16_f32 v24, v18, v19
	v_cvt_pk_bf16_f32 v25, v20, v21
	global_store_dwordx4 v[146:147], v[22:25], off offset:256
	s_mov_b64 s[58:59], 0x20000
	v_lshl_add_u64 v[146:147], v[146:147], 0, s[58:59]
	s_waitcnt vmcnt(4)
	v_lshlrev_b32_e32 v178, 16, v162
	v_and_b32_e32 v162, 0xffff0000, v162
	v_lshlrev_b32_e32 v179, 16, v166
	v_and_b32_e32 v166, 0xffff0000, v166
	v_mul_f32_e32 v14, 0xbfb8aa3b, v14
	v_mul_f32_e32 v15, 0xbfb8aa3b, v15
	v_mul_f32_e32 v180, 0xbfb8aa3b, v179
	v_mul_f32_e32 v181, 0xbfb8aa3b, v166
	v_exp_f32_e32 v14, v14
	v_exp_f32_e32 v15, v15
	v_exp_f32_e32 v180, v180
	v_exp_f32_e32 v181, v181
	v_add_f32_e32 v14, 1.0, v14
	v_add_f32_e32 v15, 1.0, v15
	v_add_f32_e32 v180, 1.0, v180
	v_add_f32_e32 v181, 1.0, v181
	v_rcp_f32_e32 v14, v14
	v_rcp_f32_e32 v15, v15
	v_rcp_f32_e32 v180, v180
	v_rcp_f32_e32 v181, v181
	v_mul_f32_e32 v14, v14, v178
	v_mul_f32_e32 v15, v15, v162
	v_mul_f32_e32 v180, v180, v179
	v_mul_f32_e32 v181, v181, v166
	v_mul_f32_e32 v14, v14, v180
	v_mul_f32_e32 v15, v15, v181
	v_lshlrev_b32_e32 v178, 16, v163
	v_and_b32_e32 v163, 0xffff0000, v163
	v_lshlrev_b32_e32 v179, 16, v167
	v_and_b32_e32 v167, 0xffff0000, v167
	v_mul_f32_e32 v16, 0xbfb8aa3b, v16
	v_mul_f32_e32 v17, 0xbfb8aa3b, v17
	v_mul_f32_e32 v180, 0xbfb8aa3b, v179
	v_mul_f32_e32 v181, 0xbfb8aa3b, v167
	v_exp_f32_e32 v16, v16
	v_exp_f32_e32 v17, v17
	v_exp_f32_e32 v180, v180
	v_exp_f32_e32 v181, v181
	v_add_f32_e32 v16, 1.0, v16
	v_add_f32_e32 v17, 1.0, v17
	v_add_f32_e32 v180, 1.0, v180
	v_add_f32_e32 v181, 1.0, v181
	v_rcp_f32_e32 v16, v16
	v_rcp_f32_e32 v17, v17
	v_rcp_f32_e32 v180, v180
	v_rcp_f32_e32 v181, v181
	v_mul_f32_e32 v16, v16, v178
	v_mul_f32_e32 v17, v17, v163
	v_mul_f32_e32 v180, v180, v179
	v_mul_f32_e32 v181, v181, v167
	v_mul_f32_e32 v16, v16, v180
	v_mul_f32_e32 v17, v17, v181
	v_lshlrev_b32_e32 v178, 16, v164
	v_and_b32_e32 v164, 0xffff0000, v164
	v_lshlrev_b32_e32 v179, 16, v168
	v_and_b32_e32 v168, 0xffff0000, v168
	v_mul_f32_e32 v10, 0xbfb8aa3b, v10
	v_mul_f32_e32 v11, 0xbfb8aa3b, v11
	v_mul_f32_e32 v180, 0xbfb8aa3b, v179
	v_mul_f32_e32 v181, 0xbfb8aa3b, v168
	v_exp_f32_e32 v10, v10
	v_exp_f32_e32 v11, v11
	v_exp_f32_e32 v180, v180
	v_exp_f32_e32 v181, v181
	v_add_f32_e32 v10, 1.0, v10
	v_add_f32_e32 v11, 1.0, v11
	v_add_f32_e32 v180, 1.0, v180
	v_add_f32_e32 v181, 1.0, v181
	v_rcp_f32_e32 v10, v10
	v_rcp_f32_e32 v11, v11
	v_rcp_f32_e32 v180, v180
	v_rcp_f32_e32 v181, v181
	v_mul_f32_e32 v10, v10, v178
	v_mul_f32_e32 v11, v11, v164
	v_mul_f32_e32 v180, v180, v179
	v_mul_f32_e32 v181, v181, v168
	v_mul_f32_e32 v10, v10, v180
	v_mul_f32_e32 v11, v11, v181
	v_lshlrev_b32_e32 v178, 16, v165
	v_and_b32_e32 v165, 0xffff0000, v165
	v_lshlrev_b32_e32 v179, 16, v169
	v_and_b32_e32 v169, 0xffff0000, v169
	v_mul_f32_e32 v12, 0xbfb8aa3b, v12
	v_mul_f32_e32 v13, 0xbfb8aa3b, v13
	v_mul_f32_e32 v180, 0xbfb8aa3b, v179
	v_mul_f32_e32 v181, 0xbfb8aa3b, v169
	v_exp_f32_e32 v12, v12
	v_exp_f32_e32 v13, v13
	v_exp_f32_e32 v180, v180
	v_exp_f32_e32 v181, v181
	v_add_f32_e32 v12, 1.0, v12
	v_add_f32_e32 v13, 1.0, v13
	v_add_f32_e32 v180, 1.0, v180
	v_add_f32_e32 v181, 1.0, v181
	v_rcp_f32_e32 v12, v12
	v_rcp_f32_e32 v13, v13
	v_rcp_f32_e32 v180, v180
	v_rcp_f32_e32 v181, v181
	v_mul_f32_e32 v12, v12, v178
	v_mul_f32_e32 v13, v13, v165
	v_mul_f32_e32 v180, v180, v179
	v_mul_f32_e32 v181, v181, v169
	v_mul_f32_e32 v12, v12, v180
	v_mul_f32_e32 v13, v13, v181
	v_cvt_pk_bf16_f32 v14, v14, v15
	v_cvt_pk_bf16_f32 v15, v16, v17
	v_cvt_pk_bf16_f32 v16, v10, v11
	v_cvt_pk_bf16_f32 v17, v12, v13
	global_store_dwordx4 v[146:147], v[14:17], off
	s_waitcnt vmcnt(2)
	v_lshlrev_b32_e32 v178, 16, v170
	v_and_b32_e32 v170, 0xffff0000, v170
	v_lshlrev_b32_e32 v179, 16, v174
	v_and_b32_e32 v174, 0xffff0000, v174
	v_mul_f32_e32 v6, 0xbfb8aa3b, v6
	v_mul_f32_e32 v7, 0xbfb8aa3b, v7
	v_mul_f32_e32 v180, 0xbfb8aa3b, v179
	v_mul_f32_e32 v181, 0xbfb8aa3b, v174
	v_exp_f32_e32 v6, v6
	v_exp_f32_e32 v7, v7
	v_exp_f32_e32 v180, v180
	v_exp_f32_e32 v181, v181
	v_add_f32_e32 v6, 1.0, v6
	v_add_f32_e32 v7, 1.0, v7
	v_add_f32_e32 v180, 1.0, v180
	v_add_f32_e32 v181, 1.0, v181
	v_rcp_f32_e32 v6, v6
	v_rcp_f32_e32 v7, v7
	v_rcp_f32_e32 v180, v180
	v_rcp_f32_e32 v181, v181
	v_mul_f32_e32 v6, v6, v178
	v_mul_f32_e32 v7, v7, v170
	v_mul_f32_e32 v180, v180, v179
	v_mul_f32_e32 v181, v181, v174
	v_mul_f32_e32 v6, v6, v180
	v_mul_f32_e32 v7, v7, v181
	v_lshlrev_b32_e32 v178, 16, v171
	v_and_b32_e32 v171, 0xffff0000, v171
	v_lshlrev_b32_e32 v179, 16, v175
	v_and_b32_e32 v175, 0xffff0000, v175
	v_mul_f32_e32 v8, 0xbfb8aa3b, v8
	v_mul_f32_e32 v9, 0xbfb8aa3b, v9
	v_mul_f32_e32 v180, 0xbfb8aa3b, v179
	v_mul_f32_e32 v181, 0xbfb8aa3b, v175
	v_exp_f32_e32 v8, v8
	v_exp_f32_e32 v9, v9
	v_exp_f32_e32 v180, v180
	v_exp_f32_e32 v181, v181
	v_add_f32_e32 v8, 1.0, v8
	v_add_f32_e32 v9, 1.0, v9
	v_add_f32_e32 v180, 1.0, v180
	v_add_f32_e32 v181, 1.0, v181
	v_rcp_f32_e32 v8, v8
	v_rcp_f32_e32 v9, v9
	v_rcp_f32_e32 v180, v180
	v_rcp_f32_e32 v181, v181
	v_mul_f32_e32 v8, v8, v178
	v_mul_f32_e32 v9, v9, v171
	v_mul_f32_e32 v180, v180, v179
	v_mul_f32_e32 v181, v181, v175
	v_mul_f32_e32 v8, v8, v180
	v_mul_f32_e32 v9, v9, v181
	v_lshlrev_b32_e32 v178, 16, v172
	v_and_b32_e32 v172, 0xffff0000, v172
	v_lshlrev_b32_e32 v179, 16, v176
	v_and_b32_e32 v176, 0xffff0000, v176
	v_mul_f32_e32 v2, 0xbfb8aa3b, v2
	v_mul_f32_e32 v3, 0xbfb8aa3b, v3
	v_mul_f32_e32 v180, 0xbfb8aa3b, v179
	v_mul_f32_e32 v181, 0xbfb8aa3b, v176
	v_exp_f32_e32 v2, v2
	v_exp_f32_e32 v3, v3
	v_exp_f32_e32 v180, v180
	v_exp_f32_e32 v181, v181
	v_add_f32_e32 v2, 1.0, v2
	v_add_f32_e32 v3, 1.0, v3
	v_add_f32_e32 v180, 1.0, v180
	v_add_f32_e32 v181, 1.0, v181
	v_rcp_f32_e32 v2, v2
	v_rcp_f32_e32 v3, v3
	v_rcp_f32_e32 v180, v180
	v_rcp_f32_e32 v181, v181
	v_mul_f32_e32 v2, v2, v178
	v_mul_f32_e32 v3, v3, v172
	v_mul_f32_e32 v180, v180, v179
	v_mul_f32_e32 v181, v181, v176
	v_mul_f32_e32 v2, v2, v180
	v_mul_f32_e32 v3, v3, v181
	v_lshlrev_b32_e32 v178, 16, v173
	v_and_b32_e32 v173, 0xffff0000, v173
	v_lshlrev_b32_e32 v179, 16, v177
	v_and_b32_e32 v177, 0xffff0000, v177
	v_mul_f32_e32 v4, 0xbfb8aa3b, v4
	v_mul_f32_e32 v5, 0xbfb8aa3b, v5
	v_mul_f32_e32 v180, 0xbfb8aa3b, v179
	v_mul_f32_e32 v181, 0xbfb8aa3b, v177
	v_exp_f32_e32 v4, v4
	v_exp_f32_e32 v5, v5
	v_exp_f32_e32 v180, v180
	v_exp_f32_e32 v181, v181
	v_add_f32_e32 v4, 1.0, v4
	v_add_f32_e32 v5, 1.0, v5
	v_add_f32_e32 v180, 1.0, v180
	v_add_f32_e32 v181, 1.0, v181
	v_rcp_f32_e32 v4, v4
	v_rcp_f32_e32 v5, v5
	v_rcp_f32_e32 v180, v180
	v_rcp_f32_e32 v181, v181
	v_mul_f32_e32 v4, v4, v178
	v_mul_f32_e32 v5, v5, v173
	v_mul_f32_e32 v180, v180, v179
	v_mul_f32_e32 v181, v181, v177
	v_mul_f32_e32 v4, v4, v180
	v_mul_f32_e32 v5, v5, v181
	v_cvt_pk_bf16_f32 v6, v6, v7
	v_cvt_pk_bf16_f32 v7, v8, v9
	v_cvt_pk_bf16_f32 v8, v2, v3
	v_cvt_pk_bf16_f32 v9, v4, v5
	global_store_dwordx4 v[146:147], v[6:9], off offset:256
	s_andn2_b64 vcc, exec, s[38:39]
	s_mov_b64 s[4:5], -1
	s_cbranch_vccnz .LBB0_686
	s_andn2_b64 vcc, exec, s[42:43]
	s_cbranch_vccnz .LBB0_685
	s_barrier
	s_branch .LBB0_685
	s_nop 0
	s_nop 0
	s_nop 0
	s_nop 0
	s_nop 0
	s_nop 0
	s_nop 0
	s_nop 0
	s_nop 0
	s_nop 0
	s_nop 0
	s_nop 0
	s_nop 0
	s_nop 0
	s_nop 0
	s_nop 0
	s_nop 0
	s_nop 0
	s_nop 0
	s_nop 0
	s_nop 0
	s_nop 0
	s_nop 0
	s_nop 0
	s_nop 0
.LBB0_698:
	v_readlane_b32 s60, v255, 0
	s_waitcnt vmcnt(0)
	v_readlane_b32 s61, v255, 1
	v_readlane_b32 s70, v254, 62
	v_readlane_b32 s60, v255, 6
	v_readlane_b32 s71, v254, 63
	v_readlane_b32 s62, v255, 2
	v_readlane_b32 s63, v255, 3
	v_readlane_b32 s61, v255, 7
	s_barrier
